# t5 + DPP/permlane-swap row reductions in post/norm/final phases and DPP cumsum in scan S0 (replacing serialized ds_bpermute chains)
# speedup vs baseline: 1.0053x; 1.0053x over previous
.LBB0_461:
	s_add_i32 s5, s4, 0xffffe000
	s_ashr_i32 s5, s5, 10
	s_add_i32 s5, s5, 1
	s_cmpk_gt_i32 s4, 0x1fff
	v_lshl_add_u64 v[34:35], s[6:7], 0, v[102:103]
	s_cselect_b32 s5, s5, 0
	v_add_co_u32_e32 v34, vcc, 0x27a00000, v34
	v_mad_i64_i32 v[36:37], s[8:9], s5, v245, v[98:99]
	s_nop 0
	v_addc_co_u32_e32 v35, vcc, 0, v35, vcc
	v_add_co_u32_e32 v70, vcc, 0x2000, v36
	s_nop 1
	v_addc_co_u32_e32 v71, vcc, 0, v37, vcc
	global_load_dwordx4 v[90:93], v[36:37], off
	global_load_dwordx4 v[82:85], v[36:37], off offset:1024
	global_load_dwordx4 v[94:97], v[70:71], off
	global_load_dwordx4 v[86:89], v[70:71], off offset:1024
	global_load_dwordx2 v[114:115], v[34:35], off
	global_load_dwordx2 v[116:117], v[34:35], off offset:512
	global_load_dwordx2 v[120:121], v[34:35], off offset:1024
	global_load_dwordx2 v[104:105], v[34:35], off offset:1536
	global_load_dwordx4 v[74:77], v[36:37], off offset:2048
	global_load_dwordx4 v[66:69], v[36:37], off offset:3072
	v_add_co_u32_e32 v38, vcc, s97, v36
	s_nop 1
	v_addc_co_u32_e32 v39, vcc, 0, v37, vcc
	v_add_co_u32_e32 v40, vcc, s91, v36
	s_nop 1
	v_addc_co_u32_e32 v41, vcc, 0, v37, vcc
	global_load_dwordx4 v[58:61], v[38:39], off
	global_load_dwordx4 v[50:53], v[38:39], off offset:1024
	global_load_dwordx4 v[62:65], v[40:41], off
	global_load_dwordx4 v[54:57], v[40:41], off offset:1024
	global_load_dwordx2 v[122:123], v[34:35], off offset:2048
	global_load_dwordx2 v[146:147], v[34:35], off offset:2560
	global_load_dwordx2 v[148:149], v[34:35], off offset:3072
	global_load_dwordx2 v[108:109], v[34:35], off offset:3584
	global_load_dwordx4 v[42:45], v[38:39], off offset:2048
	s_nop 0
	global_load_dwordx4 v[34:37], v[38:39], off offset:3072
	global_load_dwordx4 v[46:49], v[40:41], off offset:2048
	s_nop 0
	global_load_dwordx4 v[38:41], v[40:41], off offset:3072
	s_nop 0
	global_load_dwordx4 v[78:81], v[70:71], off offset:2048
	s_nop 0
	global_load_dwordx4 v[70:73], v[70:71], off offset:3072
	s_waitcnt vmcnt(14)
	v_lshlrev_b32_e32 v113, 16, v104
	v_and_b32_e32 v111, 0xffff0000, v104
	v_lshlrev_b32_e32 v118, 16, v105
	v_and_b32_e32 v119, 0xffff0000, v105
	s_waitcnt vmcnt(6)
	v_lshlrev_b32_e32 v107, 16, v108
	v_and_b32_e32 v105, 0xffff0000, v108
	v_lshlrev_b32_e32 v108, 16, v109
	v_and_b32_e32 v109, 0xffff0000, v109
	v_and_b32_e32 v139, 0xffff0000, v115
	v_and_b32_e32 v137, 0xffff0000, v114
	v_lshlrev_b32_e32 v138, 16, v115
	v_mul_f32_e32 v0, v139, v139
	v_lshlrev_b32_e32 v136, 16, v114
	v_pk_fma_f32 v[114:115], v[138:139], v[138:139], v[0:1] op_sel_hi:[1,1,0]
	v_and_b32_e32 v135, 0xffff0000, v117
	v_and_b32_e32 v134, 0xffff0000, v116
	v_mul_f32_e32 v0, v137, v137
	v_lshlrev_b32_e32 v133, 16, v117
	v_lshlrev_b32_e32 v132, 16, v116
	v_pk_mul_f32 v[116:117], v[134:135], v[134:135]
	v_lshlrev_b32_e32 v128, 16, v120
	v_and_b32_e32 v129, 0xffff0000, v120
	v_lshlrev_b32_e32 v130, 16, v121
	v_and_b32_e32 v131, 0xffff0000, v121
	v_pk_fma_f32 v[120:121], v[136:137], v[136:137], v[0:1] op_sel_hi:[1,1,0]
	v_pk_fma_f32 v[116:117], v[132:133], v[132:133], v[116:117]
	v_mov_b32_e32 v112, v120
	v_mov_b32_e32 v124, v114
	v_mov_b32_e32 v125, v113
	v_mul_f32_e32 v104, v111, v111
	v_pk_add_f32 v[114:115], v[120:121], v[114:115]
	v_pk_mul_f32 v[120:121], v[112:113], v[124:125]
	v_pk_add_f32 v[116:117], v[116:117], v[116:117] op_sel:[0,1] op_sel_hi:[1,0]
	v_mov_b32_e32 v115, v121
	v_mov_b32_e32 v117, v104
	v_mul_f32_e32 v0, v129, v129
	v_pk_add_f32 v[114:115], v[114:115], v[116:117]
	v_pk_fma_f32 v[116:117], v[128:129], v[128:129], v[0:1] op_sel_hi:[1,1,0]
	v_mul_f32_e32 v0, v131, v131
	v_mul_f32_e32 v106, v118, v118
	v_mul_f32_e32 v110, v119, v119
	v_pk_fma_f32 v[120:121], v[130:131], v[130:131], v[0:1] op_sel_hi:[1,1,0]
	v_mov_b32_e32 v117, v106
	v_mov_b32_e32 v121, v110
	v_pk_add_f32 v[116:117], v[116:117], v[120:121]
	v_and_b32_e32 v127, 0xffff0000, v123
	v_and_b32_e32 v126, 0xffff0000, v122
	v_pk_add_f32 v[150:151], v[114:115], v[116:117]
	v_lshlrev_b32_e32 v125, 16, v123
	v_lshlrev_b32_e32 v124, 16, v122
	v_pk_mul_f32 v[114:115], v[126:127], v[126:127]
	v_and_b32_e32 v123, 0xffff0000, v147
	v_pk_fma_f32 v[114:115], v[124:125], v[124:125], v[114:115]
	v_and_b32_e32 v122, 0xffff0000, v146
	v_pk_add_f32 v[152:153], v[114:115], v[114:115] op_sel:[0,1] op_sel_hi:[1,0]
	v_lshlrev_b32_e32 v121, 16, v147
	v_lshlrev_b32_e32 v120, 16, v146
	v_pk_mul_f32 v[114:115], v[122:123], v[122:123]
	v_lshlrev_b32_e32 v116, 16, v149
	v_pk_fma_f32 v[146:147], v[120:121], v[120:121], v[114:115]
	v_lshlrev_b32_e32 v114, 16, v148
	v_and_b32_e32 v115, 0xffff0000, v148
	v_and_b32_e32 v117, 0xffff0000, v149
	v_pk_add_f32 v[148:149], v[150:151], v[150:151] op_sel:[0,1] op_sel_hi:[1,0]
	v_mov_b32_e32 v150, v152
	v_mov_b32_e32 v106, v148
	v_mov_b32_e32 v151, v107
	v_mul_f32_e32 v0, v105, v105
	v_pk_add_f32 v[148:149], v[148:149], v[152:153]
	v_pk_mul_f32 v[150:151], v[106:107], v[150:151]
	v_pk_add_f32 v[146:147], v[146:147], v[146:147] op_sel:[0,1] op_sel_hi:[1,0]
	v_mov_b32_e32 v149, v151
	v_mov_b32_e32 v147, v0
	v_mul_f32_e32 v0, v115, v115
	v_pk_add_f32 v[146:147], v[148:149], v[146:147]
	v_pk_fma_f32 v[148:149], v[114:115], v[114:115], v[0:1] op_sel_hi:[1,1,0]
	v_mul_f32_e32 v0, v117, v117
	v_mul_f32_e32 v104, v108, v108
	v_mul_f32_e32 v110, v109, v109
	v_pk_fma_f32 v[150:151], v[116:117], v[116:117], v[0:1] op_sel_hi:[1,1,0]
	v_mov_b32_e32 v149, v104
	v_mov_b32_e32 v151, v110
	v_pk_add_f32 v[148:149], v[148:149], v[150:151]
	v_pk_add_f32 v[94:95], v[94:95], 1.0 op_sel_hi:[1,0]
	v_pk_add_f32 v[146:147], v[146:147], v[148:149]
	v_pk_add_f32 v[96:97], v[96:97], 1.0 op_sel_hi:[1,0]
	v_add_f32_e32 v0, v146, v147
	v_lshl_add_u64 v[146:147], s[6:7], 0, v[100:101]
	v_pk_add_f32 v[88:89], v[88:89], 1.0 op_sel_hi:[1,0]
	v_pk_add_f32 v[86:87], v[86:87], 1.0 op_sel_hi:[1,0]
	s_waitcnt vmcnt(1)
	v_pk_add_f32 v[80:81], v[80:81], 1.0 op_sel_hi:[1,0]
	s_nop 1
	v_add_f32_dpp v0, v0, v0 quad_perm:[1,0,3,2] row_mask:0xf bank_mask:0xf
	v_pk_add_f32 v[78:79], v[78:79], 1.0 op_sel_hi:[1,0]
	v_mov_b32_e32 v110, v113
	s_waitcnt vmcnt(0)
	v_pk_add_f32 v[72:73], v[72:73], 1.0 op_sel_hi:[1,0]
	v_pk_add_f32 v[70:71], v[70:71], 1.0 op_sel_hi:[1,0]
	s_nop 1
	v_add_f32_dpp v0, v0, v0 quad_perm:[2,3,0,1] row_mask:0xf bank_mask:0xf
	v_pk_add_f32 v[64:65], v[64:65], 1.0 op_sel_hi:[1,0]
	v_pk_add_f32 v[62:63], v[62:63], 1.0 op_sel_hi:[1,0]
	v_pk_add_f32 v[56:57], v[56:57], 1.0 op_sel_hi:[1,0]
	v_pk_add_f32 v[54:55], v[54:55], 1.0 op_sel_hi:[1,0]
	s_nop 1
	v_add_f32_dpp v0, v0, v0 row_half_mirror row_mask:0xf bank_mask:0xf
	v_pk_add_f32 v[48:49], v[48:49], 1.0 op_sel_hi:[1,0]
	v_pk_add_f32 v[46:47], v[46:47], 1.0 op_sel_hi:[1,0]
	v_readlane_b32 s8, v254, 13
	s_add_i32 s4, s4, s8
	s_nop 1
	v_add_f32_dpp v0, v0, v0 row_mirror row_mask:0xf bank_mask:0xf
	v_pk_add_f32 v[40:41], v[40:41], 1.0 op_sel_hi:[1,0]
	v_pk_add_f32 v[38:39], v[38:39], 1.0 op_sel_hi:[1,0]
	s_add_u32 s6, s6, s86
	s_addc_u32 s7, s7, s87
	v_mov_b32_e32 v104, v0
	s_nop 1
	v_permlane16_swap_b32 v0, v104
	v_add_f32_e32 v0, v0, v104
	s_cmpk_lt_i32 s4, 0x2800
	v_readlane_b32 s9, v254, 14
	v_mov_b32_e32 v104, v0
	s_nop 1
	v_permlane32_swap_b32 v0, v104
	v_add_f32_e32 v0, v0, v104
	v_fmamk_f32 v0, v0, 0x3a000000, v224
	v_rsq_f32_e32 v0, v0
	v_mov_b32_e32 v104, v107
	v_pk_mul_f32 v[136:137], v[0:1], v[136:137] op_sel_hi:[0,1]
	v_pk_mul_f32 v[138:139], v[0:1], v[138:139] op_sel_hi:[0,1]
	v_pk_mul_f32 v[136:137], v[2:3], v[136:137]
	v_pk_mul_f32 v[138:139], v[4:5], v[138:139]
	v_pk_fma_f32 v[90:91], v[94:95], v[136:137], v[90:91]
	v_pk_fma_f32 v[92:93], v[96:97], v[138:139], v[92:93]
	v_cvt_pk_bf16_f32 v94, v90, v91
	v_add_co_u32_e32 v90, vcc, s51, v146
	v_cvt_pk_bf16_f32 v95, v92, v93
	s_nop 0
	v_addc_co_u32_e32 v91, vcc, 0, v147, vcc
	v_mov_b32_e32 v92, v133
	v_mov_b32_e32 v93, v135
	v_mov_b32_e32 v133, v134
	global_store_dwordx2 v[90:91], v[94:95], off
	v_pk_mul_f32 v[92:93], v[0:1], v[92:93] op_sel_hi:[0,1]
	v_pk_mul_f32 v[94:95], v[0:1], v[132:133] op_sel_hi:[0,1]
	v_pk_mul_f32 v[94:95], v[6:7], v[94:95]
	v_pk_mul_f32 v[92:93], v[8:9], v[92:93]
	v_pk_fma_f32 v[82:83], v[86:87], v[94:95], v[82:83]
	v_pk_fma_f32 v[84:85], v[88:89], v[92:93], v[84:85]
	v_cvt_pk_bf16_f32 v82, v82, v83
	v_cvt_pk_bf16_f32 v83, v84, v85
	global_store_dwordx2 v[90:91], v[82:83], off offset:512
	v_pk_mul_f32 v[82:83], v[0:1], v[130:131] op_sel_hi:[0,1]
	v_pk_mul_f32 v[84:85], v[0:1], v[128:129] op_sel_hi:[0,1]
	v_pk_mul_f32 v[84:85], v[10:11], v[84:85]
	v_pk_mul_f32 v[82:83], v[12:13], v[82:83]
	v_pk_fma_f32 v[74:75], v[78:79], v[84:85], v[74:75]
	v_pk_fma_f32 v[76:77], v[80:81], v[82:83], v[76:77]
	v_cvt_pk_bf16_f32 v74, v74, v75
	v_cvt_pk_bf16_f32 v75, v76, v77
	global_store_dwordx2 v[90:91], v[74:75], off offset:1024
	v_pk_mul_f32 v[74:75], v[118:119], v[0:1] op_sel_hi:[1,0]
	v_pk_mul_f32 v[76:77], v[110:111], v[0:1] op_sel_hi:[1,0]
	v_pk_mul_f32 v[74:75], v[16:17], v[74:75]
	v_pk_mul_f32 v[76:77], v[14:15], v[76:77]
	v_pk_fma_f32 v[68:69], v[72:73], v[74:75], v[68:69]
	v_pk_fma_f32 v[66:67], v[70:71], v[76:77], v[66:67]
	s_nop 0
	v_cvt_pk_bf16_f32 v66, v66, v67
	v_cvt_pk_bf16_f32 v67, v68, v69
	global_store_dwordx2 v[90:91], v[66:67], off offset:1536
	v_mov_b32_e32 v66, v125
	v_mov_b32_e32 v67, v127
	v_mov_b32_e32 v125, v126
	v_pk_mul_f32 v[66:67], v[0:1], v[66:67] op_sel_hi:[0,1]
	v_pk_mul_f32 v[68:69], v[0:1], v[124:125] op_sel_hi:[0,1]
	v_pk_mul_f32 v[68:69], v[18:19], v[68:69]
	v_pk_mul_f32 v[66:67], v[20:21], v[66:67]
	v_pk_fma_f32 v[58:59], v[62:63], v[68:69], v[58:59]
	v_pk_fma_f32 v[60:61], v[64:65], v[66:67], v[60:61]
	v_cvt_pk_bf16_f32 v58, v58, v59
	v_cvt_pk_bf16_f32 v59, v60, v61
	global_store_dwordx2 v[90:91], v[58:59], off offset:2048
	v_mov_b32_e32 v58, v121
	v_mov_b32_e32 v59, v123
	v_mov_b32_e32 v121, v122
	v_pk_mul_f32 v[58:59], v[0:1], v[58:59] op_sel_hi:[0,1]
	v_pk_mul_f32 v[60:61], v[0:1], v[120:121] op_sel_hi:[0,1]
	v_pk_mul_f32 v[60:61], v[22:23], v[60:61]
	v_pk_mul_f32 v[58:59], v[24:25], v[58:59]
	v_pk_fma_f32 v[50:51], v[54:55], v[60:61], v[50:51]
	v_pk_fma_f32 v[52:53], v[56:57], v[58:59], v[52:53]
	v_cvt_pk_bf16_f32 v50, v50, v51
	v_cvt_pk_bf16_f32 v51, v52, v53
	global_store_dwordx2 v[90:91], v[50:51], off offset:2560
	v_pk_mul_f32 v[50:51], v[0:1], v[116:117] op_sel_hi:[0,1]
	v_pk_mul_f32 v[52:53], v[0:1], v[114:115] op_sel_hi:[0,1]
	v_pk_mul_f32 v[52:53], v[26:27], v[52:53]
	v_pk_mul_f32 v[50:51], v[28:29], v[50:51]
	v_pk_fma_f32 v[42:43], v[46:47], v[52:53], v[42:43]
	v_pk_fma_f32 v[44:45], v[48:49], v[50:51], v[44:45]
	v_cvt_pk_bf16_f32 v42, v42, v43
	v_cvt_pk_bf16_f32 v43, v44, v45
	global_store_dwordx2 v[90:91], v[42:43], off offset:3072
	v_pk_mul_f32 v[42:43], v[108:109], v[0:1] op_sel_hi:[1,0]
	v_pk_mul_f32 v[44:45], v[104:105], v[0:1] op_sel_hi:[1,0]
	v_pk_mul_f32 v[42:43], v[32:33], v[42:43]
	v_pk_mul_f32 v[44:45], v[30:31], v[44:45]
	v_pk_fma_f32 v[36:37], v[40:41], v[42:43], v[36:37]
	v_pk_fma_f32 v[34:35], v[38:39], v[44:45], v[34:35]
	s_nop 0
	v_cvt_pk_bf16_f32 v34, v34, v35
	v_cvt_pk_bf16_f32 v35, v36, v37
	global_store_dwordx2 v[90:91], v[34:35], off offset:3584
	s_cbranch_scc1 .LBB0_461

.LBB0_992:
	s_add_i32 s4, s8, 0xffffe000
	s_ashr_i32 s4, s4, 10
	s_add_i32 s4, s4, 1
	s_cmpk_gt_i32 s8, 0x1fff
	v_lshl_add_u64 v[34:35], s[10:11], 0, v[102:103]
	s_cselect_b32 s4, s4, 0
	v_add_co_u32_e32 v34, vcc, 0x27a00000, v34
	v_mad_i64_i32 v[36:37], s[4:5], s4, v245, v[98:99]
	s_nop 0
	v_addc_co_u32_e32 v35, vcc, 0, v35, vcc
	v_add_co_u32_e32 v70, vcc, 0x2000, v36
	s_nop 1
	v_addc_co_u32_e32 v71, vcc, 0, v37, vcc
	global_load_dwordx4 v[90:93], v[36:37], off
	global_load_dwordx4 v[82:85], v[36:37], off offset:1024
	global_load_dwordx4 v[94:97], v[70:71], off
	global_load_dwordx4 v[86:89], v[70:71], off offset:1024
	global_load_dwordx2 v[114:115], v[34:35], off
	global_load_dwordx2 v[116:117], v[34:35], off offset:512
	global_load_dwordx2 v[120:121], v[34:35], off offset:1024
	global_load_dwordx2 v[104:105], v[34:35], off offset:1536
	global_load_dwordx4 v[74:77], v[36:37], off offset:2048
	global_load_dwordx4 v[66:69], v[36:37], off offset:3072
	v_add_co_u32_e32 v38, vcc, s97, v36
	s_nop 1
	v_addc_co_u32_e32 v39, vcc, 0, v37, vcc
	v_add_co_u32_e32 v40, vcc, s91, v36
	s_nop 1
	v_addc_co_u32_e32 v41, vcc, 0, v37, vcc
	global_load_dwordx4 v[58:61], v[38:39], off
	global_load_dwordx4 v[50:53], v[38:39], off offset:1024
	global_load_dwordx4 v[62:65], v[40:41], off
	global_load_dwordx4 v[54:57], v[40:41], off offset:1024
	global_load_dwordx2 v[122:123], v[34:35], off offset:2048
	global_load_dwordx2 v[146:147], v[34:35], off offset:2560
	global_load_dwordx2 v[148:149], v[34:35], off offset:3072
	global_load_dwordx2 v[108:109], v[34:35], off offset:3584
	global_load_dwordx4 v[42:45], v[38:39], off offset:2048
	s_nop 0
	global_load_dwordx4 v[34:37], v[38:39], off offset:3072
	global_load_dwordx4 v[46:49], v[40:41], off offset:2048
	s_nop 0
	global_load_dwordx4 v[38:41], v[40:41], off offset:3072
	s_nop 0
	global_load_dwordx4 v[78:81], v[70:71], off offset:2048
	s_nop 0
	global_load_dwordx4 v[70:73], v[70:71], off offset:3072
	s_waitcnt vmcnt(14)
	v_lshlrev_b32_e32 v113, 16, v104
	v_and_b32_e32 v111, 0xffff0000, v104
	v_lshlrev_b32_e32 v118, 16, v105
	v_and_b32_e32 v119, 0xffff0000, v105
	s_waitcnt vmcnt(6)
	v_lshlrev_b32_e32 v107, 16, v108
	v_and_b32_e32 v105, 0xffff0000, v108
	v_lshlrev_b32_e32 v108, 16, v109
	v_and_b32_e32 v109, 0xffff0000, v109
	v_and_b32_e32 v139, 0xffff0000, v115
	v_and_b32_e32 v137, 0xffff0000, v114
	v_lshlrev_b32_e32 v138, 16, v115
	v_mul_f32_e32 v0, v139, v139
	v_lshlrev_b32_e32 v136, 16, v114
	v_pk_fma_f32 v[114:115], v[138:139], v[138:139], v[0:1] op_sel_hi:[1,1,0]
	v_and_b32_e32 v135, 0xffff0000, v117
	v_and_b32_e32 v134, 0xffff0000, v116
	v_mul_f32_e32 v0, v137, v137
	v_lshlrev_b32_e32 v133, 16, v117
	v_lshlrev_b32_e32 v132, 16, v116
	v_pk_mul_f32 v[116:117], v[134:135], v[134:135]
	v_lshlrev_b32_e32 v128, 16, v120
	v_and_b32_e32 v129, 0xffff0000, v120
	v_lshlrev_b32_e32 v130, 16, v121
	v_and_b32_e32 v131, 0xffff0000, v121
	v_pk_fma_f32 v[120:121], v[136:137], v[136:137], v[0:1] op_sel_hi:[1,1,0]
	v_pk_fma_f32 v[116:117], v[132:133], v[132:133], v[116:117]
	v_mov_b32_e32 v112, v120
	v_mov_b32_e32 v124, v114
	v_mov_b32_e32 v125, v113
	v_mul_f32_e32 v104, v111, v111
	v_pk_add_f32 v[114:115], v[120:121], v[114:115]
	v_pk_mul_f32 v[120:121], v[112:113], v[124:125]
	v_pk_add_f32 v[116:117], v[116:117], v[116:117] op_sel:[0,1] op_sel_hi:[1,0]
	v_mov_b32_e32 v115, v121
	v_mov_b32_e32 v117, v104
	v_mul_f32_e32 v0, v129, v129
	v_pk_add_f32 v[114:115], v[114:115], v[116:117]
	v_pk_fma_f32 v[116:117], v[128:129], v[128:129], v[0:1] op_sel_hi:[1,1,0]
	v_mul_f32_e32 v0, v131, v131
	v_mul_f32_e32 v106, v118, v118
	v_mul_f32_e32 v110, v119, v119
	v_pk_fma_f32 v[120:121], v[130:131], v[130:131], v[0:1] op_sel_hi:[1,1,0]
	v_mov_b32_e32 v117, v106
	v_mov_b32_e32 v121, v110
	v_pk_add_f32 v[116:117], v[116:117], v[120:121]
	v_and_b32_e32 v127, 0xffff0000, v123
	v_and_b32_e32 v126, 0xffff0000, v122
	v_pk_add_f32 v[150:151], v[114:115], v[116:117]
	v_lshlrev_b32_e32 v125, 16, v123
	v_lshlrev_b32_e32 v124, 16, v122
	v_pk_mul_f32 v[114:115], v[126:127], v[126:127]
	v_and_b32_e32 v123, 0xffff0000, v147
	v_pk_fma_f32 v[114:115], v[124:125], v[124:125], v[114:115]
	v_and_b32_e32 v122, 0xffff0000, v146
	v_pk_add_f32 v[152:153], v[114:115], v[114:115] op_sel:[0,1] op_sel_hi:[1,0]
	v_lshlrev_b32_e32 v121, 16, v147
	v_lshlrev_b32_e32 v120, 16, v146
	v_pk_mul_f32 v[114:115], v[122:123], v[122:123]
	v_lshlrev_b32_e32 v116, 16, v149
	v_pk_fma_f32 v[146:147], v[120:121], v[120:121], v[114:115]
	v_lshlrev_b32_e32 v114, 16, v148
	v_and_b32_e32 v115, 0xffff0000, v148
	v_and_b32_e32 v117, 0xffff0000, v149
	v_pk_add_f32 v[148:149], v[150:151], v[150:151] op_sel:[0,1] op_sel_hi:[1,0]
	v_mov_b32_e32 v150, v152
	v_mov_b32_e32 v106, v148
	v_mov_b32_e32 v151, v107
	v_mul_f32_e32 v0, v105, v105
	v_pk_add_f32 v[148:149], v[148:149], v[152:153]
	v_pk_mul_f32 v[150:151], v[106:107], v[150:151]
	v_pk_add_f32 v[146:147], v[146:147], v[146:147] op_sel:[0,1] op_sel_hi:[1,0]
	v_mov_b32_e32 v149, v151
	v_mov_b32_e32 v147, v0
	v_mul_f32_e32 v0, v115, v115
	v_pk_add_f32 v[146:147], v[148:149], v[146:147]
	v_pk_fma_f32 v[148:149], v[114:115], v[114:115], v[0:1] op_sel_hi:[1,1,0]
	v_mul_f32_e32 v0, v117, v117
	v_mul_f32_e32 v104, v108, v108
	v_mul_f32_e32 v110, v109, v109
	v_pk_fma_f32 v[150:151], v[116:117], v[116:117], v[0:1] op_sel_hi:[1,1,0]
	v_mov_b32_e32 v149, v104
	v_mov_b32_e32 v151, v110
	v_pk_add_f32 v[148:149], v[148:149], v[150:151]
	v_pk_add_f32 v[94:95], v[94:95], 1.0 op_sel_hi:[1,0]
	v_pk_add_f32 v[146:147], v[146:147], v[148:149]
	v_pk_add_f32 v[96:97], v[96:97], 1.0 op_sel_hi:[1,0]
	v_add_f32_e32 v0, v146, v147
	v_lshl_add_u64 v[146:147], s[10:11], 0, v[100:101]
	v_pk_add_f32 v[88:89], v[88:89], 1.0 op_sel_hi:[1,0]
	v_pk_add_f32 v[86:87], v[86:87], 1.0 op_sel_hi:[1,0]
	s_waitcnt vmcnt(1)
	v_pk_add_f32 v[80:81], v[80:81], 1.0 op_sel_hi:[1,0]
	s_nop 1
	v_add_f32_dpp v0, v0, v0 quad_perm:[1,0,3,2] row_mask:0xf bank_mask:0xf
	v_pk_add_f32 v[78:79], v[78:79], 1.0 op_sel_hi:[1,0]
	v_mov_b32_e32 v110, v113
	s_waitcnt vmcnt(0)
	v_pk_add_f32 v[72:73], v[72:73], 1.0 op_sel_hi:[1,0]
	v_pk_add_f32 v[70:71], v[70:71], 1.0 op_sel_hi:[1,0]
	s_nop 1
	v_add_f32_dpp v0, v0, v0 quad_perm:[2,3,0,1] row_mask:0xf bank_mask:0xf
	v_pk_add_f32 v[64:65], v[64:65], 1.0 op_sel_hi:[1,0]
	v_pk_add_f32 v[62:63], v[62:63], 1.0 op_sel_hi:[1,0]
	v_pk_add_f32 v[56:57], v[56:57], 1.0 op_sel_hi:[1,0]
	v_pk_add_f32 v[54:55], v[54:55], 1.0 op_sel_hi:[1,0]
	s_nop 1
	v_add_f32_dpp v0, v0, v0 row_half_mirror row_mask:0xf bank_mask:0xf
	v_pk_add_f32 v[48:49], v[48:49], 1.0 op_sel_hi:[1,0]
	v_pk_add_f32 v[46:47], v[46:47], 1.0 op_sel_hi:[1,0]
	v_readlane_b32 s4, v254, 13
	s_add_i32 s8, s8, s4
	s_nop 1
	v_add_f32_dpp v0, v0, v0 row_mirror row_mask:0xf bank_mask:0xf
	v_pk_add_f32 v[40:41], v[40:41], 1.0 op_sel_hi:[1,0]
	v_pk_add_f32 v[38:39], v[38:39], 1.0 op_sel_hi:[1,0]
	s_add_u32 s10, s10, s86
	s_addc_u32 s11, s11, s87
	v_mov_b32_e32 v104, v0
	s_nop 1
	v_permlane16_swap_b32 v0, v104
	v_add_f32_e32 v0, v0, v104
	s_cmpk_lt_i32 s8, 0x2800
	v_readlane_b32 s5, v254, 14
	v_mov_b32_e32 v104, v0
	s_nop 1
	v_permlane32_swap_b32 v0, v104
	v_add_f32_e32 v0, v0, v104
	v_fmamk_f32 v0, v0, 0x3a000000, v224
	v_rsq_f32_e32 v0, v0
	v_mov_b32_e32 v104, v107
	v_pk_mul_f32 v[136:137], v[0:1], v[136:137] op_sel_hi:[0,1]
	v_pk_mul_f32 v[138:139], v[0:1], v[138:139] op_sel_hi:[0,1]
	v_pk_mul_f32 v[136:137], v[10:11], v[136:137]
	v_pk_mul_f32 v[138:139], v[12:13], v[138:139]
	v_pk_fma_f32 v[90:91], v[94:95], v[136:137], v[90:91]
	v_pk_fma_f32 v[92:93], v[96:97], v[138:139], v[92:93]
	v_cvt_pk_bf16_f32 v94, v90, v91
	v_add_co_u32_e32 v90, vcc, s51, v146
	v_cvt_pk_bf16_f32 v95, v92, v93
	s_nop 0
	v_addc_co_u32_e32 v91, vcc, 0, v147, vcc
	v_mov_b32_e32 v92, v133
	v_mov_b32_e32 v93, v135
	v_mov_b32_e32 v133, v134
	global_store_dwordx2 v[90:91], v[94:95], off
	v_pk_mul_f32 v[92:93], v[0:1], v[92:93] op_sel_hi:[0,1]
	v_pk_mul_f32 v[94:95], v[0:1], v[132:133] op_sel_hi:[0,1]
	v_pk_mul_f32 v[94:95], v[2:3], v[94:95]
	v_pk_mul_f32 v[92:93], v[4:5], v[92:93]
	v_pk_fma_f32 v[82:83], v[86:87], v[94:95], v[82:83]
	v_pk_fma_f32 v[84:85], v[88:89], v[92:93], v[84:85]
	v_cvt_pk_bf16_f32 v82, v82, v83
	v_cvt_pk_bf16_f32 v83, v84, v85
	global_store_dwordx2 v[90:91], v[82:83], off offset:512
	v_pk_mul_f32 v[82:83], v[0:1], v[130:131] op_sel_hi:[0,1]
	v_pk_mul_f32 v[84:85], v[0:1], v[128:129] op_sel_hi:[0,1]
	v_pk_mul_f32 v[84:85], v[6:7], v[84:85]
	v_pk_mul_f32 v[82:83], v[8:9], v[82:83]
	v_pk_fma_f32 v[74:75], v[78:79], v[84:85], v[74:75]
	v_pk_fma_f32 v[76:77], v[80:81], v[82:83], v[76:77]
	v_cvt_pk_bf16_f32 v74, v74, v75
	v_cvt_pk_bf16_f32 v75, v76, v77
	global_store_dwordx2 v[90:91], v[74:75], off offset:1024
	v_pk_mul_f32 v[74:75], v[118:119], v[0:1] op_sel_hi:[1,0]
	v_pk_mul_f32 v[76:77], v[110:111], v[0:1] op_sel_hi:[1,0]
	v_pk_mul_f32 v[74:75], v[16:17], v[74:75]
	v_pk_mul_f32 v[76:77], v[14:15], v[76:77]
	v_pk_fma_f32 v[68:69], v[72:73], v[74:75], v[68:69]
	v_pk_fma_f32 v[66:67], v[70:71], v[76:77], v[66:67]
	s_nop 0
	v_cvt_pk_bf16_f32 v66, v66, v67
	v_cvt_pk_bf16_f32 v67, v68, v69
	global_store_dwordx2 v[90:91], v[66:67], off offset:1536
	v_mov_b32_e32 v66, v125
	v_mov_b32_e32 v67, v127
	v_mov_b32_e32 v125, v126
	v_pk_mul_f32 v[66:67], v[0:1], v[66:67] op_sel_hi:[0,1]
	v_pk_mul_f32 v[68:69], v[0:1], v[124:125] op_sel_hi:[0,1]
	v_pk_mul_f32 v[68:69], v[18:19], v[68:69]
	v_pk_mul_f32 v[66:67], v[20:21], v[66:67]
	v_pk_fma_f32 v[58:59], v[62:63], v[68:69], v[58:59]
	v_pk_fma_f32 v[60:61], v[64:65], v[66:67], v[60:61]
	v_cvt_pk_bf16_f32 v58, v58, v59
	v_cvt_pk_bf16_f32 v59, v60, v61
	global_store_dwordx2 v[90:91], v[58:59], off offset:2048
	v_mov_b32_e32 v58, v121
	v_mov_b32_e32 v59, v123
	v_mov_b32_e32 v121, v122
	v_pk_mul_f32 v[58:59], v[0:1], v[58:59] op_sel_hi:[0,1]
	v_pk_mul_f32 v[60:61], v[0:1], v[120:121] op_sel_hi:[0,1]
	v_pk_mul_f32 v[60:61], v[22:23], v[60:61]
	v_pk_mul_f32 v[58:59], v[24:25], v[58:59]
	v_pk_fma_f32 v[50:51], v[54:55], v[60:61], v[50:51]
	v_pk_fma_f32 v[52:53], v[56:57], v[58:59], v[52:53]
	v_cvt_pk_bf16_f32 v50, v50, v51
	v_cvt_pk_bf16_f32 v51, v52, v53
	global_store_dwordx2 v[90:91], v[50:51], off offset:2560
	v_pk_mul_f32 v[50:51], v[0:1], v[116:117] op_sel_hi:[0,1]
	v_pk_mul_f32 v[52:53], v[0:1], v[114:115] op_sel_hi:[0,1]
	v_pk_mul_f32 v[52:53], v[26:27], v[52:53]
	v_pk_mul_f32 v[50:51], v[28:29], v[50:51]
	v_pk_fma_f32 v[42:43], v[46:47], v[52:53], v[42:43]
	v_pk_fma_f32 v[44:45], v[48:49], v[50:51], v[44:45]
	v_cvt_pk_bf16_f32 v42, v42, v43
	v_cvt_pk_bf16_f32 v43, v44, v45
	global_store_dwordx2 v[90:91], v[42:43], off offset:3072
	v_pk_mul_f32 v[42:43], v[108:109], v[0:1] op_sel_hi:[1,0]
	v_pk_mul_f32 v[44:45], v[104:105], v[0:1] op_sel_hi:[1,0]
	v_pk_mul_f32 v[42:43], v[32:33], v[42:43]
	v_pk_mul_f32 v[44:45], v[30:31], v[44:45]
	v_pk_fma_f32 v[36:37], v[40:41], v[42:43], v[36:37]
	v_pk_fma_f32 v[34:35], v[38:39], v[44:45], v[34:35]
	s_nop 0
	v_cvt_pk_bf16_f32 v34, v34, v35
	v_cvt_pk_bf16_f32 v35, v36, v37
	global_store_dwordx2 v[90:91], v[34:35], off offset:3584
	s_cbranch_scc1 .LBB0_992

.LBB0_1382:
	s_add_i32 s4, 0, 0x11000
	v_mov_b32_e32 v113, s63
	v_mov_b32_e32 v88, s80
	v_mov_b32_e32 v109, s4
	v_mov_b32_e32 v2, s46
	v_mov_b32_e32 v3, s47
	v_mov_b32_e32 v117, s94
	v_mov_b32_e32 v89, s95
	v_mov_b32_e32 v107, s96
	v_mov_b32_e32 v62, v119
	v_mov_b32_e32 v114, 0
	v_mov_b32_e32 v0, v105
	s_and_b64 vcc, exec, s[8:9]
	s_cbranch_vccnz .LBB0_1384
	v_lshl_add_u32 v64, v62, 2, v107
	s_waitcnt vmcnt(1)
	v_mov_b32_e32 v60, v115
	s_nop 1
	v_add_f32_dpp v60, v60, v60 row_shr:1 row_mask:0xf bank_mask:0xf
	s_nop 1
	v_add_f32_dpp v60, v60, v60 row_shr:2 row_mask:0xf bank_mask:0xf
	s_nop 1
	v_add_f32_dpp v60, v60, v60 row_shr:4 row_mask:0xf bank_mask:0xf
	s_nop 1
	v_add_f32_dpp v60, v60, v60 row_shr:8 row_mask:0xf bank_mask:0xf
	s_nop 1
	v_add_f32_dpp v60, v60, v60 row_bcast:15 row_mask:0xa bank_mask:0xf
	s_nop 1
	v_add_f32_dpp v60, v60, v60 row_bcast:31 row_mask:0xc bank_mask:0xf
	s_nop 1
	v_readlane_b32 s4, v60, 63
	v_mul_f32_e32 v63, 0x3fb8aa3b, v60
	v_exp_f32_e32 v63, v63
	s_nop 0
	v_sub_f32_e32 v61, s4, v60
	v_mul_f32_e32 v61, 0x3fb8aa3b, v61
	v_exp_f32_e32 v61, v61
	s_waitcnt vmcnt(0)
	ds_write2st64_b32 v64, v60, v118 offset1:1
	ds_write2st64_b32 v64, v63, v61 offset0:2 offset1:3
	v_mul_f32_e32 v60, v118, v63
	ds_write2st64_b32 v64, v60, v118 offset0:4 offset1:5

.LBB0_1461:
	v_readlane_b32 s4, v252, 0
	v_readlane_b32 s5, v252, 1
	s_nop 1
	v_lshl_add_u64 v[32:33], s[4:5], 0, v[6:7]
	v_add_co_u32_e32 v24, vcc, 0x47580000, v32
	v_lshl_add_u64 v[28:29], s[4:5], 0, v[22:23]
	s_nop 0
	v_addc_co_u32_e32 v25, vcc, 0, v33, vcc
	v_add_co_u32_e32 v26, vcc, 0x49d80000, v32
	global_load_dwordx2 v[60:61], v[24:25], off
	s_nop 0
	v_addc_co_u32_e32 v27, vcc, 0, v33, vcc
	global_load_dwordx2 v[62:63], v[26:27], off
	global_load_dwordx2 v[64:65], v[28:29], off
	global_load_dwordx2 v[66:67], v[24:25], off offset:512
	global_load_dwordx2 v[68:69], v[26:27], off offset:512
	v_lshl_add_u64 v[28:29], s[4:5], 0, v[20:21]
	global_load_dwordx2 v[70:71], v[28:29], off
	global_load_dwordx2 v[72:73], v[24:25], off offset:1024
	global_load_dwordx2 v[74:75], v[26:27], off offset:1024
	v_lshl_add_u64 v[28:29], s[4:5], 0, v[18:19]
	global_load_dwordx2 v[76:77], v[28:29], off
	global_load_dwordx2 v[54:55], v[24:25], off offset:1536
	global_load_dwordx2 v[52:53], v[26:27], off offset:1536
	v_lshl_add_u64 v[28:29], s[4:5], 0, v[16:17]
	global_load_dwordx2 v[50:51], v[28:29], off
	global_load_dwordx2 v[48:49], v[24:25], off offset:2048
	global_load_dwordx2 v[46:47], v[26:27], off offset:2048
	v_lshl_add_u64 v[28:29], s[4:5], 0, v[14:15]
	global_load_dwordx2 v[44:45], v[28:29], off
	global_load_dwordx2 v[42:43], v[24:25], off offset:2560
	global_load_dwordx2 v[40:41], v[26:27], off offset:2560
	v_lshl_add_u64 v[28:29], s[4:5], 0, v[12:13]
	global_load_dwordx2 v[38:39], v[28:29], off
	global_load_dwordx2 v[36:37], v[24:25], off offset:3072
	global_load_dwordx2 v[34:35], v[26:27], off offset:3072
	v_lshl_add_u64 v[28:29], s[4:5], 0, v[10:11]
	v_add_co_u32_e32 v32, vcc, s51, v32
	global_load_dwordx2 v[30:31], v[28:29], off
	s_nop 0
	global_load_dwordx2 v[28:29], v[24:25], off offset:3584
	s_nop 0
	global_load_dwordx2 v[26:27], v[26:27], off offset:3584
	v_lshl_add_u64 v[24:25], s[4:5], 0, v[8:9]
	v_addc_co_u32_e32 v33, vcc, 0, v33, vcc
	global_load_dwordx2 v[24:25], v[24:25], off
	v_readlane_b32 s4, v254, 13
	s_add_i32 s8, s8, s4
	v_lshl_add_u64 v[6:7], v[6:7], 0, s[86:87]
	v_lshl_add_u64 v[8:9], v[8:9], 0, s[6:7]
	v_lshl_add_u64 v[10:11], v[10:11], 0, s[6:7]
	v_lshl_add_u64 v[12:13], v[12:13], 0, s[6:7]
	v_lshl_add_u64 v[14:15], v[14:15], 0, s[6:7]
	v_lshl_add_u64 v[16:17], v[16:17], 0, s[6:7]
	v_lshl_add_u64 v[18:19], v[18:19], 0, s[6:7]
	v_lshl_add_u64 v[20:21], v[20:21], 0, s[6:7]
	v_lshl_add_u64 v[22:23], v[22:23], 0, s[6:7]
	s_cmpk_lt_i32 s8, 0x2800
	v_readlane_b32 s5, v254, 14
	s_waitcnt vmcnt(23)
	v_lshlrev_b32_e32 v78, 16, v60
	v_and_b32_e32 v79, 0xffff0000, v60
	v_lshlrev_b32_e32 v60, 16, v61
	s_waitcnt vmcnt(22)
	v_lshlrev_b32_e32 v80, 16, v62
	v_and_b32_e32 v81, 0xffff0000, v62
	v_and_b32_e32 v61, 0xffff0000, v61
	v_lshlrev_b32_e32 v62, 16, v63
	v_and_b32_e32 v63, 0xffff0000, v63
	v_pk_add_f32 v[78:79], v[78:79], v[80:81]
	v_pk_add_f32 v[60:61], v[60:61], v[62:63]
	v_mov_b32_e32 v80, v79
	v_mov_b32_e32 v81, v61
	v_mov_b32_e32 v62, v78
	v_mov_b32_e32 v63, v60
	v_pk_mul_f32 v[80:81], v[80:81], v[80:81]
	s_nop 0
	v_pk_fma_f32 v[62:63], v[62:63], v[62:63], v[80:81]
	s_nop 0
	v_add_f32_e32 v62, v62, v63
	s_nop 1
	v_add_f32_dpp v62, v62, v62 quad_perm:[1,0,3,2] row_mask:0xf bank_mask:0xf
	s_nop 1
	v_add_f32_dpp v62, v62, v62 quad_perm:[2,3,0,1] row_mask:0xf bank_mask:0xf
	s_nop 1
	v_add_f32_dpp v62, v62, v62 row_half_mirror row_mask:0xf bank_mask:0xf
	s_nop 1
	v_add_f32_dpp v62, v62, v62 row_mirror row_mask:0xf bank_mask:0xf
	v_mov_b32_e32 v63, v62
	s_nop 1
	v_permlane16_swap_b32 v62, v63
	v_add_f32_e32 v62, v62, v63
	v_fmamk_f32 v62, v62, 0x3c000000, v224
	v_rsq_f32_e32 v62, v62
	s_nop 0
	v_pk_mul_f32 v[78:79], v[78:79], v[62:63] op_sel_hi:[1,0]
	v_pk_mul_f32 v[60:61], v[60:61], v[62:63] op_sel_hi:[1,0]
	v_pk_mul_f32 v[62:63], v[2:3], v[78:79]
	s_waitcnt vmcnt(21)
	v_lshlrev_b32_e32 v78, 16, v64
	v_and_b32_e32 v79, 0xffff0000, v64
	v_mul_f32_e32 v64, 0xbfb8aa3b, v78
	v_exp_f32_e32 v64, v64
	v_pk_mul_f32 v[60:61], v[4:5], v[60:61]
	v_add_f32_e32 v64, 1.0, v64
	v_rcp_f32_e32 v80, v64
	v_mul_f32_e32 v64, 0xbfb8aa3b, v79
	v_exp_f32_e32 v64, v64
	s_nop 0
	v_add_f32_e32 v64, 1.0, v64
	v_rcp_f32_e32 v81, v64
	v_lshlrev_b32_e32 v64, 16, v65
	v_and_b32_e32 v65, 0xffff0000, v65
	v_pk_mul_f32 v[78:79], v[80:81], v[78:79]
	s_nop 0
	v_pk_mul_f32 v[62:63], v[78:79], v[62:63]
	v_mul_f32_e32 v78, 0xbfb8aa3b, v64
	v_mul_f32_e32 v79, 0xbfb8aa3b, v65
	v_exp_f32_e32 v78, v78
	v_exp_f32_e32 v79, v79
	v_cvt_pk_bf16_f32 v62, v62, v63
	v_add_f32_e32 v78, 1.0, v78
	v_add_f32_e32 v79, 1.0, v79
	v_rcp_f32_e32 v78, v78
	v_rcp_f32_e32 v79, v79
	s_nop 0
	v_pk_mul_f32 v[64:65], v[78:79], v[64:65]
	s_nop 0
	v_pk_mul_f32 v[60:61], v[64:65], v[60:61]
	s_waitcnt vmcnt(19)
	v_lshlrev_b32_e32 v64, 16, v69
	v_cvt_pk_bf16_f32 v63, v60, v61
	global_store_dwordx2 v[32:33], v[62:63], off
	v_lshlrev_b32_e32 v60, 16, v66
	v_and_b32_e32 v61, 0xffff0000, v66
	v_lshlrev_b32_e32 v62, 16, v68
	v_and_b32_e32 v63, 0xffff0000, v68
	v_pk_add_f32 v[60:61], v[60:61], v[62:63]
	v_lshlrev_b32_e32 v62, 16, v67
	v_and_b32_e32 v63, 0xffff0000, v67
	v_and_b32_e32 v65, 0xffff0000, v69
	v_pk_add_f32 v[62:63], v[62:63], v[64:65]
	v_mov_b32_e32 v66, v61
	v_mov_b32_e32 v67, v63
	v_mov_b32_e32 v64, v60
	v_mov_b32_e32 v65, v62
	v_pk_mul_f32 v[66:67], v[66:67], v[66:67]
	s_nop 0
	v_pk_fma_f32 v[64:65], v[64:65], v[64:65], v[66:67]
	s_nop 0
	v_add_f32_e32 v64, v64, v65
	s_nop 1
	v_add_f32_dpp v64, v64, v64 quad_perm:[1,0,3,2] row_mask:0xf bank_mask:0xf
	s_nop 1
	v_add_f32_dpp v64, v64, v64 quad_perm:[2,3,0,1] row_mask:0xf bank_mask:0xf
	s_nop 1
	v_add_f32_dpp v64, v64, v64 row_half_mirror row_mask:0xf bank_mask:0xf
	s_nop 1
	v_add_f32_dpp v64, v64, v64 row_mirror row_mask:0xf bank_mask:0xf
	v_mov_b32_e32 v65, v64
	s_nop 1
	v_permlane16_swap_b32 v64, v65
	v_add_f32_e32 v64, v64, v65
	v_fmamk_f32 v64, v64, 0x3c000000, v224
	v_rsq_f32_e32 v64, v64
	s_nop 0
	v_pk_mul_f32 v[60:61], v[60:61], v[64:65] op_sel_hi:[1,0]
	v_pk_mul_f32 v[62:63], v[62:63], v[64:65] op_sel_hi:[1,0]
	s_waitcnt vmcnt(19)
	v_lshlrev_b32_e32 v64, 16, v70
	v_and_b32_e32 v65, 0xffff0000, v70
	v_mul_f32_e32 v66, 0xbfb8aa3b, v64
	v_mul_f32_e32 v67, 0xbfb8aa3b, v65
	v_exp_f32_e32 v66, v66
	v_exp_f32_e32 v67, v67
	v_pk_mul_f32 v[60:61], v[2:3], v[60:61]
	v_pk_mul_f32 v[62:63], v[4:5], v[62:63]
	v_add_f32_e32 v66, 1.0, v66
	v_add_f32_e32 v67, 1.0, v67
	v_rcp_f32_e32 v66, v66
	v_rcp_f32_e32 v67, v67
	s_nop 0
	v_pk_mul_f32 v[64:65], v[66:67], v[64:65]
	s_nop 0
	v_pk_mul_f32 v[60:61], v[64:65], v[60:61]
	v_lshlrev_b32_e32 v64, 16, v71
	v_and_b32_e32 v65, 0xffff0000, v71
	v_mul_f32_e32 v66, 0xbfb8aa3b, v64
	v_mul_f32_e32 v67, 0xbfb8aa3b, v65
	v_exp_f32_e32 v66, v66
	v_exp_f32_e32 v67, v67
	v_cvt_pk_bf16_f32 v60, v60, v61
	v_add_f32_e32 v66, 1.0, v66
	v_add_f32_e32 v67, 1.0, v67
	v_rcp_f32_e32 v66, v66
	v_rcp_f32_e32 v67, v67
	s_nop 0
	v_pk_mul_f32 v[64:65], v[66:67], v[64:65]
	s_nop 0
	v_pk_mul_f32 v[62:63], v[64:65], v[62:63]
	s_waitcnt vmcnt(17)
	v_lshlrev_b32_e32 v64, 16, v75
	v_cvt_pk_bf16_f32 v61, v62, v63
	global_store_dwordx2 v[32:33], v[60:61], off offset:512
	v_lshlrev_b32_e32 v60, 16, v72
	v_and_b32_e32 v61, 0xffff0000, v72
	v_lshlrev_b32_e32 v62, 16, v74
	v_and_b32_e32 v63, 0xffff0000, v74
	v_pk_add_f32 v[60:61], v[60:61], v[62:63]
	v_lshlrev_b32_e32 v62, 16, v73
	v_and_b32_e32 v63, 0xffff0000, v73
	v_and_b32_e32 v65, 0xffff0000, v75
	v_pk_add_f32 v[62:63], v[62:63], v[64:65]
	v_mov_b32_e32 v66, v61
	v_mov_b32_e32 v67, v63
	v_mov_b32_e32 v64, v60
	v_mov_b32_e32 v65, v62
	v_pk_mul_f32 v[66:67], v[66:67], v[66:67]
	s_nop 0
	v_pk_fma_f32 v[64:65], v[64:65], v[64:65], v[66:67]
	s_nop 0
	v_add_f32_e32 v64, v64, v65
	s_nop 1
	v_add_f32_dpp v64, v64, v64 quad_perm:[1,0,3,2] row_mask:0xf bank_mask:0xf
	s_nop 1
	v_add_f32_dpp v64, v64, v64 quad_perm:[2,3,0,1] row_mask:0xf bank_mask:0xf
	s_nop 1
	v_add_f32_dpp v64, v64, v64 row_half_mirror row_mask:0xf bank_mask:0xf
	s_nop 1
	v_add_f32_dpp v64, v64, v64 row_mirror row_mask:0xf bank_mask:0xf
	v_mov_b32_e32 v65, v64
	s_nop 1
	v_permlane16_swap_b32 v64, v65
	v_add_f32_e32 v64, v64, v65
	v_fmamk_f32 v64, v64, 0x3c000000, v224
	v_rsq_f32_e32 v64, v64
	s_nop 0
	v_pk_mul_f32 v[60:61], v[60:61], v[64:65] op_sel_hi:[1,0]
	v_pk_mul_f32 v[62:63], v[62:63], v[64:65] op_sel_hi:[1,0]
	s_waitcnt vmcnt(17)
	v_lshlrev_b32_e32 v64, 16, v76
	v_and_b32_e32 v65, 0xffff0000, v76
	v_mul_f32_e32 v66, 0xbfb8aa3b, v64
	v_mul_f32_e32 v67, 0xbfb8aa3b, v65
	v_exp_f32_e32 v66, v66
	v_exp_f32_e32 v67, v67
	v_pk_mul_f32 v[60:61], v[2:3], v[60:61]
	v_pk_mul_f32 v[62:63], v[4:5], v[62:63]
	v_add_f32_e32 v66, 1.0, v66
	v_add_f32_e32 v67, 1.0, v67
	v_rcp_f32_e32 v66, v66
	v_rcp_f32_e32 v67, v67
	s_nop 0
	v_pk_mul_f32 v[64:65], v[66:67], v[64:65]
	s_nop 0
	v_pk_mul_f32 v[60:61], v[64:65], v[60:61]
	v_lshlrev_b32_e32 v64, 16, v77
	v_and_b32_e32 v65, 0xffff0000, v77
	v_mul_f32_e32 v66, 0xbfb8aa3b, v64
	v_mul_f32_e32 v67, 0xbfb8aa3b, v65
	v_exp_f32_e32 v66, v66
	v_exp_f32_e32 v67, v67
	v_cvt_pk_bf16_f32 v60, v60, v61
	v_add_f32_e32 v66, 1.0, v66
	v_add_f32_e32 v67, 1.0, v67
	v_rcp_f32_e32 v66, v66
	v_rcp_f32_e32 v67, v67
	s_nop 0
	v_pk_mul_f32 v[64:65], v[66:67], v[64:65]
	s_nop 0
	v_pk_mul_f32 v[62:63], v[64:65], v[62:63]
	s_nop 0
	v_cvt_pk_bf16_f32 v61, v62, v63
	global_store_dwordx2 v[32:33], v[60:61], off offset:1024
	s_waitcnt vmcnt(17)
	v_lshlrev_b32_e32 v60, 16, v54
	v_and_b32_e32 v61, 0xffff0000, v54
	s_waitcnt vmcnt(16)
	v_lshlrev_b32_e32 v62, 16, v52
	v_and_b32_e32 v63, 0xffff0000, v52
	v_lshlrev_b32_e32 v54, 16, v55
	v_and_b32_e32 v55, 0xffff0000, v55
	v_lshlrev_b32_e32 v52, 16, v53
	v_and_b32_e32 v53, 0xffff0000, v53
	v_pk_add_f32 v[60:61], v[60:61], v[62:63]
	v_pk_add_f32 v[52:53], v[54:55], v[52:53]
	v_mov_b32_e32 v62, v61
	v_mov_b32_e32 v63, v53
	v_mov_b32_e32 v54, v60
	v_mov_b32_e32 v55, v52
	v_pk_mul_f32 v[62:63], v[62:63], v[62:63]
	s_nop 0
	v_pk_fma_f32 v[54:55], v[54:55], v[54:55], v[62:63]
	s_nop 0
	v_add_f32_e32 v54, v54, v55
	s_nop 1
	v_add_f32_dpp v54, v54, v54 quad_perm:[1,0,3,2] row_mask:0xf bank_mask:0xf
	s_nop 1
	v_add_f32_dpp v54, v54, v54 quad_perm:[2,3,0,1] row_mask:0xf bank_mask:0xf
	s_nop 1
	v_add_f32_dpp v54, v54, v54 row_half_mirror row_mask:0xf bank_mask:0xf
	s_nop 1
	v_add_f32_dpp v54, v54, v54 row_mirror row_mask:0xf bank_mask:0xf
	v_mov_b32_e32 v55, v54
	s_nop 1
	v_permlane16_swap_b32 v54, v55
	v_add_f32_e32 v54, v54, v55
	v_fmamk_f32 v54, v54, 0x3c000000, v224
	v_rsq_f32_e32 v54, v54
	s_nop 0
	v_pk_mul_f32 v[60:61], v[60:61], v[54:55] op_sel_hi:[1,0]
	v_pk_mul_f32 v[52:53], v[52:53], v[54:55] op_sel_hi:[1,0]
	v_pk_mul_f32 v[54:55], v[2:3], v[60:61]
	s_waitcnt vmcnt(15)
	v_lshlrev_b32_e32 v60, 16, v50
	v_and_b32_e32 v61, 0xffff0000, v50
	v_mul_f32_e32 v50, 0xbfb8aa3b, v60
	v_exp_f32_e32 v50, v50
	v_pk_mul_f32 v[52:53], v[4:5], v[52:53]
	v_add_f32_e32 v50, 1.0, v50
	v_rcp_f32_e32 v62, v50
	v_mul_f32_e32 v50, 0xbfb8aa3b, v61
	v_exp_f32_e32 v50, v50
	s_nop 0
	v_add_f32_e32 v50, 1.0, v50
	v_rcp_f32_e32 v63, v50
	v_lshlrev_b32_e32 v50, 16, v51
	v_and_b32_e32 v51, 0xffff0000, v51
	v_pk_mul_f32 v[60:61], v[62:63], v[60:61]
	s_nop 0
	v_pk_mul_f32 v[54:55], v[60:61], v[54:55]
	v_mul_f32_e32 v60, 0xbfb8aa3b, v50
	v_mul_f32_e32 v61, 0xbfb8aa3b, v51
	v_exp_f32_e32 v60, v60
	v_exp_f32_e32 v61, v61
	v_add_f32_e32 v60, 1.0, v60
	v_add_f32_e32 v61, 1.0, v61
	v_rcp_f32_e32 v60, v60
	v_rcp_f32_e32 v61, v61
	s_nop 0
	v_pk_mul_f32 v[50:51], v[60:61], v[50:51]
	s_nop 0
	v_pk_mul_f32 v[50:51], v[50:51], v[52:53]
	v_cvt_pk_bf16_f32 v52, v54, v55
	v_cvt_pk_bf16_f32 v53, v50, v51
	global_store_dwordx2 v[32:33], v[52:53], off offset:1536
	s_waitcnt vmcnt(15)
	v_lshlrev_b32_e32 v50, 16, v48
	v_and_b32_e32 v51, 0xffff0000, v48
	s_waitcnt vmcnt(14)
	v_lshlrev_b32_e32 v52, 16, v46
	v_and_b32_e32 v53, 0xffff0000, v46
	v_lshlrev_b32_e32 v48, 16, v49
	v_and_b32_e32 v49, 0xffff0000, v49
	v_lshlrev_b32_e32 v46, 16, v47
	v_and_b32_e32 v47, 0xffff0000, v47
	v_pk_add_f32 v[50:51], v[50:51], v[52:53]
	v_pk_add_f32 v[46:47], v[48:49], v[46:47]
	v_mov_b32_e32 v52, v51
	v_mov_b32_e32 v53, v47
	v_mov_b32_e32 v48, v50
	v_mov_b32_e32 v49, v46
	v_pk_mul_f32 v[52:53], v[52:53], v[52:53]
	s_nop 0
	v_pk_fma_f32 v[48:49], v[48:49], v[48:49], v[52:53]
	s_nop 0
	v_add_f32_e32 v48, v48, v49
	s_nop 1
	v_add_f32_dpp v48, v48, v48 quad_perm:[1,0,3,2] row_mask:0xf bank_mask:0xf
	s_nop 1
	v_add_f32_dpp v48, v48, v48 quad_perm:[2,3,0,1] row_mask:0xf bank_mask:0xf
	s_nop 1
	v_add_f32_dpp v48, v48, v48 row_half_mirror row_mask:0xf bank_mask:0xf
	s_nop 1
	v_add_f32_dpp v48, v48, v48 row_mirror row_mask:0xf bank_mask:0xf
	v_mov_b32_e32 v49, v48
	s_nop 1
	v_permlane16_swap_b32 v48, v49
	v_add_f32_e32 v48, v48, v49
	v_fmamk_f32 v48, v48, 0x3c000000, v224
	v_rsq_f32_e32 v48, v48
	s_nop 0
	v_pk_mul_f32 v[50:51], v[50:51], v[48:49] op_sel_hi:[1,0]
	v_pk_mul_f32 v[46:47], v[46:47], v[48:49] op_sel_hi:[1,0]
	v_pk_mul_f32 v[48:49], v[2:3], v[50:51]
	s_waitcnt vmcnt(13)
	v_lshlrev_b32_e32 v50, 16, v44
	v_and_b32_e32 v51, 0xffff0000, v44
	v_mul_f32_e32 v44, 0xbfb8aa3b, v50
	v_exp_f32_e32 v44, v44
	v_pk_mul_f32 v[46:47], v[4:5], v[46:47]
	v_add_f32_e32 v44, 1.0, v44
	v_rcp_f32_e32 v52, v44
	v_mul_f32_e32 v44, 0xbfb8aa3b, v51
	v_exp_f32_e32 v44, v44
	s_nop 0
	v_add_f32_e32 v44, 1.0, v44
	v_rcp_f32_e32 v53, v44
	v_lshlrev_b32_e32 v44, 16, v45
	v_and_b32_e32 v45, 0xffff0000, v45
	v_pk_mul_f32 v[50:51], v[52:53], v[50:51]
	s_nop 0
	v_pk_mul_f32 v[48:49], v[50:51], v[48:49]
	v_mul_f32_e32 v50, 0xbfb8aa3b, v44
	v_mul_f32_e32 v51, 0xbfb8aa3b, v45
	v_exp_f32_e32 v50, v50
	v_exp_f32_e32 v51, v51
	v_add_f32_e32 v50, 1.0, v50
	v_add_f32_e32 v51, 1.0, v51
	v_rcp_f32_e32 v50, v50
	v_rcp_f32_e32 v51, v51
	s_nop 0
	v_pk_mul_f32 v[44:45], v[50:51], v[44:45]
	s_nop 0
	v_pk_mul_f32 v[44:45], v[44:45], v[46:47]
	v_cvt_pk_bf16_f32 v46, v48, v49
	v_cvt_pk_bf16_f32 v47, v44, v45
	global_store_dwordx2 v[32:33], v[46:47], off offset:2048
	s_waitcnt vmcnt(13)
	v_lshlrev_b32_e32 v44, 16, v42
	v_and_b32_e32 v45, 0xffff0000, v42
	s_waitcnt vmcnt(12)
	v_lshlrev_b32_e32 v46, 16, v40
	v_and_b32_e32 v47, 0xffff0000, v40
	v_lshlrev_b32_e32 v42, 16, v43
	v_and_b32_e32 v43, 0xffff0000, v43
	v_lshlrev_b32_e32 v40, 16, v41
	v_and_b32_e32 v41, 0xffff0000, v41
	v_pk_add_f32 v[44:45], v[44:45], v[46:47]
	v_pk_add_f32 v[40:41], v[42:43], v[40:41]
	v_mov_b32_e32 v46, v45
	v_mov_b32_e32 v47, v41
	v_mov_b32_e32 v42, v44
	v_mov_b32_e32 v43, v40
	v_pk_mul_f32 v[46:47], v[46:47], v[46:47]
	s_nop 0
	v_pk_fma_f32 v[42:43], v[42:43], v[42:43], v[46:47]
	s_nop 0
	v_add_f32_e32 v42, v42, v43
	s_nop 1
	v_add_f32_dpp v42, v42, v42 quad_perm:[1,0,3,2] row_mask:0xf bank_mask:0xf
	s_nop 1
	v_add_f32_dpp v42, v42, v42 quad_perm:[2,3,0,1] row_mask:0xf bank_mask:0xf
	s_nop 1
	v_add_f32_dpp v42, v42, v42 row_half_mirror row_mask:0xf bank_mask:0xf
	s_nop 1
	v_add_f32_dpp v42, v42, v42 row_mirror row_mask:0xf bank_mask:0xf
	v_mov_b32_e32 v43, v42
	s_nop 1
	v_permlane16_swap_b32 v42, v43
	v_add_f32_e32 v42, v42, v43
	v_fmamk_f32 v42, v42, 0x3c000000, v224
	v_rsq_f32_e32 v42, v42
	s_nop 0
	v_pk_mul_f32 v[44:45], v[44:45], v[42:43] op_sel_hi:[1,0]
	v_pk_mul_f32 v[40:41], v[40:41], v[42:43] op_sel_hi:[1,0]
	v_pk_mul_f32 v[42:43], v[2:3], v[44:45]
	s_waitcnt vmcnt(11)
	v_lshlrev_b32_e32 v44, 16, v38
	v_and_b32_e32 v45, 0xffff0000, v38
	v_mul_f32_e32 v38, 0xbfb8aa3b, v44
	v_exp_f32_e32 v38, v38
	v_pk_mul_f32 v[40:41], v[4:5], v[40:41]
	v_add_f32_e32 v38, 1.0, v38
	v_rcp_f32_e32 v46, v38
	v_mul_f32_e32 v38, 0xbfb8aa3b, v45
	v_exp_f32_e32 v38, v38
	s_nop 0
	v_add_f32_e32 v38, 1.0, v38
	v_rcp_f32_e32 v47, v38
	v_lshlrev_b32_e32 v38, 16, v39
	v_and_b32_e32 v39, 0xffff0000, v39
	v_pk_mul_f32 v[44:45], v[46:47], v[44:45]
	s_nop 0
	v_pk_mul_f32 v[42:43], v[44:45], v[42:43]
	v_mul_f32_e32 v44, 0xbfb8aa3b, v38
	v_mul_f32_e32 v45, 0xbfb8aa3b, v39
	v_exp_f32_e32 v44, v44
	v_exp_f32_e32 v45, v45
	v_add_f32_e32 v44, 1.0, v44
	v_add_f32_e32 v45, 1.0, v45
	v_rcp_f32_e32 v44, v44
	v_rcp_f32_e32 v45, v45
	s_nop 0
	v_pk_mul_f32 v[38:39], v[44:45], v[38:39]
	s_nop 0
	v_pk_mul_f32 v[38:39], v[38:39], v[40:41]
	v_cvt_pk_bf16_f32 v40, v42, v43
	v_cvt_pk_bf16_f32 v41, v38, v39
	global_store_dwordx2 v[32:33], v[40:41], off offset:2560
	s_waitcnt vmcnt(11)
	v_lshlrev_b32_e32 v38, 16, v36
	v_and_b32_e32 v39, 0xffff0000, v36
	s_waitcnt vmcnt(10)
	v_lshlrev_b32_e32 v40, 16, v34
	v_and_b32_e32 v41, 0xffff0000, v34
	v_lshlrev_b32_e32 v36, 16, v37
	v_and_b32_e32 v37, 0xffff0000, v37
	v_lshlrev_b32_e32 v34, 16, v35
	v_and_b32_e32 v35, 0xffff0000, v35
	v_pk_add_f32 v[38:39], v[38:39], v[40:41]
	v_pk_add_f32 v[34:35], v[36:37], v[34:35]
	v_mov_b32_e32 v40, v39
	v_mov_b32_e32 v41, v35
	v_mov_b32_e32 v36, v38
	v_mov_b32_e32 v37, v34
	v_pk_mul_f32 v[40:41], v[40:41], v[40:41]
	s_nop 0
	v_pk_fma_f32 v[36:37], v[36:37], v[36:37], v[40:41]
	s_nop 0
	v_add_f32_e32 v36, v36, v37
	s_nop 1
	v_add_f32_dpp v36, v36, v36 quad_perm:[1,0,3,2] row_mask:0xf bank_mask:0xf
	s_nop 1
	v_add_f32_dpp v36, v36, v36 quad_perm:[2,3,0,1] row_mask:0xf bank_mask:0xf
	s_nop 1
	v_add_f32_dpp v36, v36, v36 row_half_mirror row_mask:0xf bank_mask:0xf
	s_nop 1
	v_add_f32_dpp v36, v36, v36 row_mirror row_mask:0xf bank_mask:0xf
	v_mov_b32_e32 v37, v36
	s_nop 1
	v_permlane16_swap_b32 v36, v37
	v_add_f32_e32 v36, v36, v37
	v_fmamk_f32 v36, v36, 0x3c000000, v224
	v_rsq_f32_e32 v36, v36
	s_nop 0
	v_pk_mul_f32 v[38:39], v[38:39], v[36:37] op_sel_hi:[1,0]
	v_pk_mul_f32 v[34:35], v[34:35], v[36:37] op_sel_hi:[1,0]
	v_pk_mul_f32 v[36:37], v[2:3], v[38:39]
	s_waitcnt vmcnt(9)
	v_lshlrev_b32_e32 v38, 16, v30
	v_and_b32_e32 v39, 0xffff0000, v30
	v_mul_f32_e32 v30, 0xbfb8aa3b, v38
	v_exp_f32_e32 v30, v30
	v_pk_mul_f32 v[34:35], v[4:5], v[34:35]
	v_add_f32_e32 v30, 1.0, v30
	v_rcp_f32_e32 v40, v30
	v_mul_f32_e32 v30, 0xbfb8aa3b, v39
	v_exp_f32_e32 v30, v30
	s_nop 0
	v_add_f32_e32 v30, 1.0, v30
	v_rcp_f32_e32 v41, v30
	v_lshlrev_b32_e32 v30, 16, v31
	v_and_b32_e32 v31, 0xffff0000, v31
	v_pk_mul_f32 v[38:39], v[40:41], v[38:39]
	s_nop 0
	v_pk_mul_f32 v[36:37], v[38:39], v[36:37]
	v_mul_f32_e32 v38, 0xbfb8aa3b, v30
	v_mul_f32_e32 v39, 0xbfb8aa3b, v31
	v_exp_f32_e32 v38, v38
	v_exp_f32_e32 v39, v39
	v_add_f32_e32 v38, 1.0, v38
	v_add_f32_e32 v39, 1.0, v39
	v_rcp_f32_e32 v38, v38
	v_rcp_f32_e32 v39, v39
	s_nop 0
	v_pk_mul_f32 v[30:31], v[38:39], v[30:31]
	s_nop 0
	v_pk_mul_f32 v[30:31], v[30:31], v[34:35]
	v_cvt_pk_bf16_f32 v34, v36, v37
	v_cvt_pk_bf16_f32 v35, v30, v31
	global_store_dwordx2 v[32:33], v[34:35], off offset:3072
	s_waitcnt vmcnt(9)
	v_lshlrev_b32_e32 v30, 16, v28
	v_and_b32_e32 v31, 0xffff0000, v28
	s_waitcnt vmcnt(8)
	v_lshlrev_b32_e32 v34, 16, v26
	v_and_b32_e32 v35, 0xffff0000, v26
	v_lshlrev_b32_e32 v28, 16, v29
	v_and_b32_e32 v29, 0xffff0000, v29
	v_lshlrev_b32_e32 v26, 16, v27
	v_and_b32_e32 v27, 0xffff0000, v27
	v_pk_add_f32 v[30:31], v[30:31], v[34:35]
	v_pk_add_f32 v[26:27], v[28:29], v[26:27]
	v_mov_b32_e32 v34, v31
	v_mov_b32_e32 v35, v27
	v_mov_b32_e32 v28, v30
	v_mov_b32_e32 v29, v26
	v_pk_mul_f32 v[34:35], v[34:35], v[34:35]
	s_nop 0
	v_pk_fma_f32 v[28:29], v[28:29], v[28:29], v[34:35]
	s_nop 0
	v_add_f32_e32 v28, v28, v29
	s_nop 1
	v_add_f32_dpp v28, v28, v28 quad_perm:[1,0,3,2] row_mask:0xf bank_mask:0xf
	s_nop 1
	v_add_f32_dpp v28, v28, v28 quad_perm:[2,3,0,1] row_mask:0xf bank_mask:0xf
	s_nop 1
	v_add_f32_dpp v28, v28, v28 row_half_mirror row_mask:0xf bank_mask:0xf
	s_nop 1
	v_add_f32_dpp v28, v28, v28 row_mirror row_mask:0xf bank_mask:0xf
	v_mov_b32_e32 v29, v28
	s_nop 1
	v_permlane16_swap_b32 v28, v29
	v_add_f32_e32 v28, v28, v29
	v_fmamk_f32 v28, v28, 0x3c000000, v224
	v_rsq_f32_e32 v28, v28
	s_nop 0
	v_pk_mul_f32 v[30:31], v[30:31], v[28:29] op_sel_hi:[1,0]
	v_pk_mul_f32 v[26:27], v[26:27], v[28:29] op_sel_hi:[1,0]
	v_pk_mul_f32 v[28:29], v[2:3], v[30:31]
	s_waitcnt vmcnt(7)
	v_lshlrev_b32_e32 v30, 16, v24
	v_and_b32_e32 v31, 0xffff0000, v24
	v_mul_f32_e32 v24, 0xbfb8aa3b, v30
	v_exp_f32_e32 v24, v24
	v_pk_mul_f32 v[26:27], v[4:5], v[26:27]
	v_add_f32_e32 v24, 1.0, v24
	v_rcp_f32_e32 v34, v24
	v_mul_f32_e32 v24, 0xbfb8aa3b, v31
	v_exp_f32_e32 v24, v24
	s_nop 0
	v_add_f32_e32 v24, 1.0, v24
	v_rcp_f32_e32 v35, v24
	v_lshlrev_b32_e32 v24, 16, v25
	v_and_b32_e32 v25, 0xffff0000, v25
	v_pk_mul_f32 v[30:31], v[34:35], v[30:31]
	s_nop 0
	v_pk_mul_f32 v[28:29], v[30:31], v[28:29]
	v_mul_f32_e32 v30, 0xbfb8aa3b, v24
	v_mul_f32_e32 v31, 0xbfb8aa3b, v25
	v_exp_f32_e32 v30, v30
	v_exp_f32_e32 v31, v31
	v_add_f32_e32 v30, 1.0, v30
	v_add_f32_e32 v31, 1.0, v31
	v_rcp_f32_e32 v30, v30
	v_rcp_f32_e32 v31, v31
	s_nop 0
	v_pk_mul_f32 v[24:25], v[30:31], v[24:25]
	s_nop 0
	v_pk_mul_f32 v[24:25], v[24:25], v[26:27]
	v_cvt_pk_bf16_f32 v26, v28, v29
	v_cvt_pk_bf16_f32 v27, v24, v25
	global_store_dwordx2 v[32:33], v[26:27], off offset:3584
	s_cbranch_scc1 .LBB0_1461

.LBB0_1600:
	s_add_i32 s5, s4, 0xffffe000
	s_ashr_i32 s5, s5, 10
	s_add_i32 s5, s5, 1
	s_cmpk_gt_i32 s4, 0x1fff
	v_lshl_add_u64 v[34:35], s[8:9], 0, v[102:103]
	s_cselect_b32 s5, s5, 0
	v_add_co_u32_e32 v34, vcc, 0x27a00000, v34
	v_mad_i64_i32 v[36:37], s[6:7], s5, v245, v[98:99]
	s_nop 0
	v_addc_co_u32_e32 v35, vcc, 0, v35, vcc
	v_add_co_u32_e32 v70, vcc, 0x2000, v36
	s_nop 1
	v_addc_co_u32_e32 v71, vcc, 0, v37, vcc
	global_load_dwordx4 v[90:93], v[36:37], off
	global_load_dwordx4 v[82:85], v[36:37], off offset:1024
	global_load_dwordx4 v[94:97], v[70:71], off
	global_load_dwordx4 v[86:89], v[70:71], off offset:1024
	global_load_dwordx2 v[114:115], v[34:35], off
	global_load_dwordx2 v[116:117], v[34:35], off offset:512
	global_load_dwordx2 v[120:121], v[34:35], off offset:1024
	global_load_dwordx2 v[104:105], v[34:35], off offset:1536
	global_load_dwordx4 v[74:77], v[36:37], off offset:2048
	global_load_dwordx4 v[66:69], v[36:37], off offset:3072
	v_add_co_u32_e32 v38, vcc, s97, v36
	s_nop 1
	v_addc_co_u32_e32 v39, vcc, 0, v37, vcc
	v_add_co_u32_e32 v40, vcc, s91, v36
	s_nop 1
	v_addc_co_u32_e32 v41, vcc, 0, v37, vcc
	global_load_dwordx4 v[58:61], v[38:39], off
	global_load_dwordx4 v[50:53], v[38:39], off offset:1024
	global_load_dwordx4 v[62:65], v[40:41], off
	global_load_dwordx4 v[54:57], v[40:41], off offset:1024
	global_load_dwordx2 v[122:123], v[34:35], off offset:2048
	global_load_dwordx2 v[146:147], v[34:35], off offset:2560
	global_load_dwordx2 v[148:149], v[34:35], off offset:3072
	global_load_dwordx2 v[108:109], v[34:35], off offset:3584
	global_load_dwordx4 v[42:45], v[38:39], off offset:2048
	s_nop 0
	global_load_dwordx4 v[34:37], v[38:39], off offset:3072
	global_load_dwordx4 v[46:49], v[40:41], off offset:2048
	s_nop 0
	global_load_dwordx4 v[38:41], v[40:41], off offset:3072
	s_nop 0
	global_load_dwordx4 v[78:81], v[70:71], off offset:2048
	s_nop 0
	global_load_dwordx4 v[70:73], v[70:71], off offset:3072
	s_waitcnt vmcnt(14)
	v_lshlrev_b32_e32 v113, 16, v104
	v_and_b32_e32 v111, 0xffff0000, v104
	v_lshlrev_b32_e32 v118, 16, v105
	v_and_b32_e32 v119, 0xffff0000, v105
	s_waitcnt vmcnt(6)
	v_lshlrev_b32_e32 v107, 16, v108
	v_and_b32_e32 v105, 0xffff0000, v108
	v_lshlrev_b32_e32 v108, 16, v109
	v_and_b32_e32 v109, 0xffff0000, v109
	v_and_b32_e32 v139, 0xffff0000, v115
	v_and_b32_e32 v137, 0xffff0000, v114
	v_lshlrev_b32_e32 v138, 16, v115
	v_mul_f32_e32 v0, v139, v139
	v_lshlrev_b32_e32 v136, 16, v114
	v_pk_fma_f32 v[114:115], v[138:139], v[138:139], v[0:1] op_sel_hi:[1,1,0]
	v_and_b32_e32 v135, 0xffff0000, v117
	v_and_b32_e32 v134, 0xffff0000, v116
	v_mul_f32_e32 v0, v137, v137
	v_lshlrev_b32_e32 v133, 16, v117
	v_lshlrev_b32_e32 v132, 16, v116
	v_pk_mul_f32 v[116:117], v[134:135], v[134:135]
	v_lshlrev_b32_e32 v128, 16, v120
	v_and_b32_e32 v129, 0xffff0000, v120
	v_lshlrev_b32_e32 v130, 16, v121
	v_and_b32_e32 v131, 0xffff0000, v121
	v_pk_fma_f32 v[120:121], v[136:137], v[136:137], v[0:1] op_sel_hi:[1,1,0]
	v_pk_fma_f32 v[116:117], v[132:133], v[132:133], v[116:117]
	v_mov_b32_e32 v112, v120
	v_mov_b32_e32 v124, v114
	v_mov_b32_e32 v125, v113
	v_mul_f32_e32 v104, v111, v111
	v_pk_add_f32 v[114:115], v[120:121], v[114:115]
	v_pk_mul_f32 v[120:121], v[112:113], v[124:125]
	v_pk_add_f32 v[116:117], v[116:117], v[116:117] op_sel:[0,1] op_sel_hi:[1,0]
	v_mov_b32_e32 v115, v121
	v_mov_b32_e32 v117, v104
	v_mul_f32_e32 v0, v129, v129
	v_pk_add_f32 v[114:115], v[114:115], v[116:117]
	v_pk_fma_f32 v[116:117], v[128:129], v[128:129], v[0:1] op_sel_hi:[1,1,0]
	v_mul_f32_e32 v0, v131, v131
	v_mul_f32_e32 v106, v118, v118
	v_mul_f32_e32 v110, v119, v119
	v_pk_fma_f32 v[120:121], v[130:131], v[130:131], v[0:1] op_sel_hi:[1,1,0]
	v_mov_b32_e32 v117, v106
	v_mov_b32_e32 v121, v110
	v_pk_add_f32 v[116:117], v[116:117], v[120:121]
	v_and_b32_e32 v127, 0xffff0000, v123
	v_and_b32_e32 v126, 0xffff0000, v122
	v_pk_add_f32 v[150:151], v[114:115], v[116:117]
	v_lshlrev_b32_e32 v125, 16, v123
	v_lshlrev_b32_e32 v124, 16, v122
	v_pk_mul_f32 v[114:115], v[126:127], v[126:127]
	v_and_b32_e32 v123, 0xffff0000, v147
	v_pk_fma_f32 v[114:115], v[124:125], v[124:125], v[114:115]
	v_and_b32_e32 v122, 0xffff0000, v146
	v_pk_add_f32 v[152:153], v[114:115], v[114:115] op_sel:[0,1] op_sel_hi:[1,0]
	v_lshlrev_b32_e32 v121, 16, v147
	v_lshlrev_b32_e32 v120, 16, v146
	v_pk_mul_f32 v[114:115], v[122:123], v[122:123]
	v_lshlrev_b32_e32 v116, 16, v149
	v_pk_fma_f32 v[146:147], v[120:121], v[120:121], v[114:115]
	v_lshlrev_b32_e32 v114, 16, v148
	v_and_b32_e32 v115, 0xffff0000, v148
	v_and_b32_e32 v117, 0xffff0000, v149
	v_pk_add_f32 v[148:149], v[150:151], v[150:151] op_sel:[0,1] op_sel_hi:[1,0]
	v_mov_b32_e32 v150, v152
	v_mov_b32_e32 v106, v148
	v_mov_b32_e32 v151, v107
	v_mul_f32_e32 v0, v105, v105
	v_pk_add_f32 v[148:149], v[148:149], v[152:153]
	v_pk_mul_f32 v[150:151], v[106:107], v[150:151]
	v_pk_add_f32 v[146:147], v[146:147], v[146:147] op_sel:[0,1] op_sel_hi:[1,0]
	v_mov_b32_e32 v149, v151
	v_mov_b32_e32 v147, v0
	v_mul_f32_e32 v0, v115, v115
	v_pk_add_f32 v[146:147], v[148:149], v[146:147]
	v_pk_fma_f32 v[148:149], v[114:115], v[114:115], v[0:1] op_sel_hi:[1,1,0]
	v_mul_f32_e32 v0, v117, v117
	v_mul_f32_e32 v104, v108, v108
	v_mul_f32_e32 v110, v109, v109
	v_pk_fma_f32 v[150:151], v[116:117], v[116:117], v[0:1] op_sel_hi:[1,1,0]
	v_mov_b32_e32 v149, v104
	v_mov_b32_e32 v151, v110
	v_pk_add_f32 v[148:149], v[148:149], v[150:151]
	v_pk_add_f32 v[94:95], v[94:95], 1.0 op_sel_hi:[1,0]
	v_pk_add_f32 v[146:147], v[146:147], v[148:149]
	v_pk_add_f32 v[96:97], v[96:97], 1.0 op_sel_hi:[1,0]
	v_add_f32_e32 v0, v146, v147
	v_lshl_add_u64 v[146:147], s[8:9], 0, v[100:101]
	v_pk_add_f32 v[88:89], v[88:89], 1.0 op_sel_hi:[1,0]
	v_pk_add_f32 v[86:87], v[86:87], 1.0 op_sel_hi:[1,0]
	s_waitcnt vmcnt(1)
	v_pk_add_f32 v[80:81], v[80:81], 1.0 op_sel_hi:[1,0]
	s_nop 1
	v_add_f32_dpp v0, v0, v0 quad_perm:[1,0,3,2] row_mask:0xf bank_mask:0xf
	v_pk_add_f32 v[78:79], v[78:79], 1.0 op_sel_hi:[1,0]
	v_mov_b32_e32 v110, v113
	s_waitcnt vmcnt(0)
	v_pk_add_f32 v[72:73], v[72:73], 1.0 op_sel_hi:[1,0]
	v_pk_add_f32 v[70:71], v[70:71], 1.0 op_sel_hi:[1,0]
	s_nop 1
	v_add_f32_dpp v0, v0, v0 quad_perm:[2,3,0,1] row_mask:0xf bank_mask:0xf
	v_pk_add_f32 v[64:65], v[64:65], 1.0 op_sel_hi:[1,0]
	v_pk_add_f32 v[62:63], v[62:63], 1.0 op_sel_hi:[1,0]
	v_pk_add_f32 v[56:57], v[56:57], 1.0 op_sel_hi:[1,0]
	v_pk_add_f32 v[54:55], v[54:55], 1.0 op_sel_hi:[1,0]
	s_nop 1
	v_add_f32_dpp v0, v0, v0 row_half_mirror row_mask:0xf bank_mask:0xf
	v_pk_add_f32 v[48:49], v[48:49], 1.0 op_sel_hi:[1,0]
	v_pk_add_f32 v[46:47], v[46:47], 1.0 op_sel_hi:[1,0]
	v_readlane_b32 s6, v254, 13
	s_add_i32 s4, s4, s6
	s_nop 1
	v_add_f32_dpp v0, v0, v0 row_mirror row_mask:0xf bank_mask:0xf
	v_pk_add_f32 v[40:41], v[40:41], 1.0 op_sel_hi:[1,0]
	v_pk_add_f32 v[38:39], v[38:39], 1.0 op_sel_hi:[1,0]
	s_add_u32 s8, s8, s86
	s_addc_u32 s9, s9, s87
	v_mov_b32_e32 v104, v0
	s_nop 1
	v_permlane16_swap_b32 v0, v104
	v_add_f32_e32 v0, v0, v104
	s_cmpk_lt_i32 s4, 0x2800
	v_readlane_b32 s7, v254, 14
	v_mov_b32_e32 v104, v0
	s_nop 1
	v_permlane32_swap_b32 v0, v104
	v_add_f32_e32 v0, v0, v104
	v_fmamk_f32 v0, v0, 0x3a000000, v224
	v_rsq_f32_e32 v0, v0
	v_mov_b32_e32 v104, v107
	v_pk_mul_f32 v[136:137], v[0:1], v[136:137] op_sel_hi:[0,1]
	v_pk_mul_f32 v[138:139], v[0:1], v[138:139] op_sel_hi:[0,1]
	v_pk_mul_f32 v[136:137], v[10:11], v[136:137]
	v_pk_mul_f32 v[138:139], v[12:13], v[138:139]
	v_pk_fma_f32 v[90:91], v[94:95], v[136:137], v[90:91]
	v_pk_fma_f32 v[92:93], v[96:97], v[138:139], v[92:93]
	v_cvt_pk_bf16_f32 v94, v90, v91
	v_add_co_u32_e32 v90, vcc, s51, v146
	v_cvt_pk_bf16_f32 v95, v92, v93
	s_nop 0
	v_addc_co_u32_e32 v91, vcc, 0, v147, vcc
	v_mov_b32_e32 v92, v133
	v_mov_b32_e32 v93, v135
	v_mov_b32_e32 v133, v134
	global_store_dwordx2 v[90:91], v[94:95], off
	v_pk_mul_f32 v[92:93], v[0:1], v[92:93] op_sel_hi:[0,1]
	v_pk_mul_f32 v[94:95], v[0:1], v[132:133] op_sel_hi:[0,1]
	v_pk_mul_f32 v[94:95], v[2:3], v[94:95]
	v_pk_mul_f32 v[92:93], v[4:5], v[92:93]
	v_pk_fma_f32 v[82:83], v[86:87], v[94:95], v[82:83]
	v_pk_fma_f32 v[84:85], v[88:89], v[92:93], v[84:85]
	v_cvt_pk_bf16_f32 v82, v82, v83
	v_cvt_pk_bf16_f32 v83, v84, v85
	global_store_dwordx2 v[90:91], v[82:83], off offset:512
	v_pk_mul_f32 v[82:83], v[0:1], v[130:131] op_sel_hi:[0,1]
	v_pk_mul_f32 v[84:85], v[0:1], v[128:129] op_sel_hi:[0,1]
	v_pk_mul_f32 v[84:85], v[6:7], v[84:85]
	v_pk_mul_f32 v[82:83], v[8:9], v[82:83]
	v_pk_fma_f32 v[74:75], v[78:79], v[84:85], v[74:75]
	v_pk_fma_f32 v[76:77], v[80:81], v[82:83], v[76:77]
	v_cvt_pk_bf16_f32 v74, v74, v75
	v_cvt_pk_bf16_f32 v75, v76, v77
	global_store_dwordx2 v[90:91], v[74:75], off offset:1024
	v_pk_mul_f32 v[74:75], v[118:119], v[0:1] op_sel_hi:[1,0]
	v_pk_mul_f32 v[76:77], v[110:111], v[0:1] op_sel_hi:[1,0]
	v_pk_mul_f32 v[74:75], v[16:17], v[74:75]
	v_pk_mul_f32 v[76:77], v[14:15], v[76:77]
	v_pk_fma_f32 v[68:69], v[72:73], v[74:75], v[68:69]
	v_pk_fma_f32 v[66:67], v[70:71], v[76:77], v[66:67]
	s_nop 0
	v_cvt_pk_bf16_f32 v66, v66, v67
	v_cvt_pk_bf16_f32 v67, v68, v69
	global_store_dwordx2 v[90:91], v[66:67], off offset:1536
	v_mov_b32_e32 v66, v125
	v_mov_b32_e32 v67, v127
	v_mov_b32_e32 v125, v126
	v_pk_mul_f32 v[66:67], v[0:1], v[66:67] op_sel_hi:[0,1]
	v_pk_mul_f32 v[68:69], v[0:1], v[124:125] op_sel_hi:[0,1]
	v_pk_mul_f32 v[68:69], v[18:19], v[68:69]
	v_pk_mul_f32 v[66:67], v[20:21], v[66:67]
	v_pk_fma_f32 v[58:59], v[62:63], v[68:69], v[58:59]
	v_pk_fma_f32 v[60:61], v[64:65], v[66:67], v[60:61]
	v_cvt_pk_bf16_f32 v58, v58, v59
	v_cvt_pk_bf16_f32 v59, v60, v61
	global_store_dwordx2 v[90:91], v[58:59], off offset:2048
	v_mov_b32_e32 v58, v121
	v_mov_b32_e32 v59, v123
	v_mov_b32_e32 v121, v122
	v_pk_mul_f32 v[58:59], v[0:1], v[58:59] op_sel_hi:[0,1]
	v_pk_mul_f32 v[60:61], v[0:1], v[120:121] op_sel_hi:[0,1]
	v_pk_mul_f32 v[60:61], v[22:23], v[60:61]
	v_pk_mul_f32 v[58:59], v[24:25], v[58:59]
	v_pk_fma_f32 v[50:51], v[54:55], v[60:61], v[50:51]
	v_pk_fma_f32 v[52:53], v[56:57], v[58:59], v[52:53]
	v_cvt_pk_bf16_f32 v50, v50, v51
	v_cvt_pk_bf16_f32 v51, v52, v53
	global_store_dwordx2 v[90:91], v[50:51], off offset:2560
	v_pk_mul_f32 v[50:51], v[0:1], v[116:117] op_sel_hi:[0,1]
	v_pk_mul_f32 v[52:53], v[0:1], v[114:115] op_sel_hi:[0,1]
	v_pk_mul_f32 v[52:53], v[26:27], v[52:53]
	v_pk_mul_f32 v[50:51], v[28:29], v[50:51]
	v_pk_fma_f32 v[42:43], v[46:47], v[52:53], v[42:43]
	v_pk_fma_f32 v[44:45], v[48:49], v[50:51], v[44:45]
	v_cvt_pk_bf16_f32 v42, v42, v43
	v_cvt_pk_bf16_f32 v43, v44, v45
	global_store_dwordx2 v[90:91], v[42:43], off offset:3072
	v_pk_mul_f32 v[42:43], v[108:109], v[0:1] op_sel_hi:[1,0]
	v_pk_mul_f32 v[44:45], v[104:105], v[0:1] op_sel_hi:[1,0]
	v_pk_mul_f32 v[42:43], v[32:33], v[42:43]
	v_pk_mul_f32 v[44:45], v[30:31], v[44:45]
	v_pk_fma_f32 v[36:37], v[40:41], v[42:43], v[36:37]
	v_pk_fma_f32 v[34:35], v[38:39], v[44:45], v[34:35]
	s_nop 0
	v_cvt_pk_bf16_f32 v34, v34, v35
	v_cvt_pk_bf16_f32 v35, v36, v37
	global_store_dwordx2 v[90:91], v[34:35], off offset:3584
	s_cbranch_scc1 .LBB0_1600

.LBB0_1867:
	global_load_dwordx2 v[36:37], v[34:35], off
	global_load_dwordx2 v[38:39], v[34:35], off offset:512
	global_load_dwordx2 v[48:49], v[34:35], off offset:1024
	global_load_dwordx2 v[50:51], v[34:35], off offset:1536
	global_load_dwordx2 v[52:53], v[34:35], off offset:2048
	global_load_dwordx2 v[54:55], v[34:35], off offset:2560
	global_load_dwordx2 v[56:57], v[34:35], off offset:3072
	global_load_dwordx2 v[58:59], v[34:35], off offset:3584
	v_readlane_b32 s4, v254, 13
	s_add_i32 s0, s0, s4
	v_lshl_add_u64 v[34:35], v[34:35], 0, s[86:87]
	s_cmpk_lt_i32 s0, 0x2800
	v_readlane_b32 s5, v254, 14
	s_waitcnt vmcnt(0)
	v_lshlrev_b32_e32 v60, 16, v36
	v_and_b32_e32 v61, 0xffff0000, v36
	v_lshlrev_b32_e32 v36, 16, v37
	v_and_b32_e32 v37, 0xffff0000, v37
	v_lshlrev_b32_e32 v63, 16, v39
	v_lshlrev_b32_e32 v62, 16, v38
	v_and_b32_e32 v39, 0xffff0000, v39
	v_and_b32_e32 v38, 0xffff0000, v38
	v_and_b32_e32 v65, 0xffff0000, v48
	v_lshlrev_b32_e32 v67, 16, v50
	v_lshlrev_b32_e32 v77, 16, v58
	v_mul_f32_e32 v66, v37, v37
	v_pk_mul_f32 v[80:81], v[38:39], v[38:39]
	v_mul_f32_e32 v76, v61, v61
	v_lshlrev_b32_e32 v64, 16, v48
	v_lshlrev_b32_e32 v48, 16, v49
	v_and_b32_e32 v49, 0xffff0000, v49
	v_mov_b32_e32 v83, v67
	v_mul_f32_e32 v82, v65, v65
	v_mov_b32_e32 v94, v62
	v_mov_b32_e32 v95, v38
	v_mov_b32_e32 v38, v63
	v_pk_fma_f32 v[100:101], v[36:37], v[36:37], v[66:67] op_sel_hi:[1,1,0]
	v_pk_fma_f32 v[62:63], v[62:63], v[62:63], v[80:81]
	v_pk_fma_f32 v[80:81], v[60:61], v[60:61], v[76:77] op_sel_hi:[1,1,0]
	v_and_b32_e32 v69, 0xffff0000, v50
	v_lshlrev_b32_e32 v50, 16, v51
	v_and_b32_e32 v51, 0xffff0000, v51
	v_mul_f32_e32 v84, v49, v49
	v_mov_b32_e32 v85, v77
	v_pk_fma_f32 v[102:103], v[64:65], v[64:65], v[82:83] op_sel_hi:[1,1,0]
	v_mov_b32_e32 v66, v80
	v_mov_b32_e32 v82, v100
	v_mul_f32_e32 v47, v69, v69
	v_mul_f32_e32 v91, v50, v50
	v_mul_f32_e32 v93, v51, v51
	v_mov_b32_e32 v68, v67
	v_pk_fma_f32 v[104:105], v[48:49], v[48:49], v[84:85] op_sel_hi:[1,1,0]
	v_pk_add_f32 v[80:81], v[80:81], v[100:101]
	v_pk_add_f32 v[62:63], v[62:63], v[62:63] op_sel:[0,1] op_sel_hi:[1,0]
	v_pk_mul_f32 v[66:67], v[66:67], v[82:83]
	v_lshlrev_b32_e32 v71, 16, v53
	v_lshlrev_b32_e32 v70, 16, v52
	v_and_b32_e32 v53, 0xffff0000, v53
	v_and_b32_e32 v52, 0xffff0000, v52
	v_mov_b32_e32 v103, v91
	v_mov_b32_e32 v105, v93
	v_mov_b32_e32 v63, v47
	v_mov_b32_e32 v81, v67
	v_pk_mul_f32 v[86:87], v[52:53], v[52:53]
	v_pk_add_f32 v[82:83], v[102:103], v[104:105]
	v_pk_add_f32 v[62:63], v[80:81], v[62:63]
	v_lshlrev_b32_e32 v73, 16, v55
	v_lshlrev_b32_e32 v72, 16, v54
	v_and_b32_e32 v55, 0xffff0000, v55
	v_and_b32_e32 v54, 0xffff0000, v54
	v_mov_b32_e32 v96, v70
	v_mov_b32_e32 v97, v52
	v_mov_b32_e32 v52, v71
	v_pk_fma_f32 v[70:71], v[70:71], v[70:71], v[86:87]
	v_pk_add_f32 v[62:63], v[62:63], v[82:83]
	v_lshlrev_b32_e32 v74, 16, v56
	v_and_b32_e32 v75, 0xffff0000, v56
	v_lshlrev_b32_e32 v56, 16, v57
	v_and_b32_e32 v57, 0xffff0000, v57
	v_pk_mul_f32 v[88:89], v[54:55], v[54:55]
	v_pk_add_f32 v[70:71], v[70:71], v[70:71] op_sel:[0,1] op_sel_hi:[1,0]
	v_pk_add_f32 v[62:63], v[62:63], v[62:63] op_sel:[0,1] op_sel_hi:[1,0]
	v_and_b32_e32 v79, 0xffff0000, v58
	v_lshlrev_b32_e32 v58, 16, v59
	v_and_b32_e32 v59, 0xffff0000, v59
	v_mul_f32_e32 v90, v75, v75
	v_mul_f32_e32 v92, v57, v57
	v_mov_b32_e32 v98, v72
	v_mov_b32_e32 v99, v54
	v_mov_b32_e32 v54, v73
	v_pk_fma_f32 v[72:73], v[72:73], v[72:73], v[88:89]
	v_mov_b32_e32 v84, v70
	v_mov_b32_e32 v76, v62
	v_mul_f32_e32 v106, v79, v79
	v_mul_f32_e32 v107, v58, v58
	v_mul_f32_e32 v108, v59, v59
	v_pk_fma_f32 v[86:87], v[74:75], v[74:75], v[90:91] op_sel_hi:[1,1,0]
	v_pk_fma_f32 v[88:89], v[56:57], v[56:57], v[92:93] op_sel_hi:[1,1,0]
	v_pk_add_f32 v[72:73], v[72:73], v[72:73] op_sel:[0,1] op_sel_hi:[1,0]
	v_pk_add_f32 v[62:63], v[62:63], v[70:71]
	v_pk_mul_f32 v[66:67], v[76:77], v[84:85]
	v_mov_b32_e32 v87, v107
	v_mov_b32_e32 v89, v108
	v_mov_b32_e32 v73, v106
	v_mov_b32_e32 v63, v67
	v_pk_add_f32 v[86:87], v[86:87], v[88:89]
	v_pk_add_f32 v[62:63], v[62:63], v[72:73]
	v_mov_b32_e32 v78, v77
	v_pk_add_f32 v[62:63], v[62:63], v[86:87]
	s_nop 0
	v_add_f32_e32 v47, v62, v63
	s_nop 1
	v_add_f32_dpp v47, v47, v47 quad_perm:[1,0,3,2] row_mask:0xf bank_mask:0xf
	s_nop 1
	v_add_f32_dpp v47, v47, v47 quad_perm:[2,3,0,1] row_mask:0xf bank_mask:0xf
	s_nop 1
	v_add_f32_dpp v47, v47, v47 row_half_mirror row_mask:0xf bank_mask:0xf
	s_nop 1
	v_add_f32_dpp v47, v47, v47 row_mirror row_mask:0xf bank_mask:0xf
	v_mov_b32_e32 v62, v47
	s_nop 1
	v_permlane16_swap_b32 v47, v62
	v_add_f32_e32 v47, v47, v62
	v_mov_b32_e32 v62, v47
	s_nop 1
	v_permlane32_swap_b32 v47, v62
	v_add_f32_e32 v47, v47, v62
	v_fmamk_f32 v47, v47, 0x3a000000, v46
	v_rsq_f32_e32 v62, v47
	s_nop 0
	v_pk_mul_f32 v[60:61], v[62:63], v[60:61] op_sel_hi:[0,1]
	v_pk_mul_f32 v[36:37], v[62:63], v[36:37] op_sel_hi:[0,1]
	v_pk_mul_f32 v[66:67], v[62:63], v[94:95] op_sel_hi:[0,1]
	v_pk_mul_f32 v[70:71], v[62:63], v[38:39] op_sel_hi:[0,1]
	v_pk_mul_f32 v[64:65], v[62:63], v[64:65] op_sel_hi:[0,1]
	v_pk_mul_f32 v[72:73], v[62:63], v[48:49] op_sel_hi:[0,1]
	v_pk_mul_f32 v[68:69], v[68:69], v[62:63] op_sel_hi:[1,0]
	v_pk_mul_f32 v[76:77], v[50:51], v[62:63] op_sel_hi:[1,0]
	v_pk_mul_f32 v[80:81], v[62:63], v[96:97] op_sel_hi:[0,1]
	v_pk_mul_f32 v[82:83], v[62:63], v[52:53] op_sel_hi:[0,1]
	v_pk_mul_f32 v[84:85], v[62:63], v[98:99] op_sel_hi:[0,1]
	v_pk_mul_f32 v[86:87], v[62:63], v[54:55] op_sel_hi:[0,1]
	v_pk_mul_f32 v[74:75], v[62:63], v[74:75] op_sel_hi:[0,1]
	v_pk_mul_f32 v[88:89], v[62:63], v[56:57] op_sel_hi:[0,1]
	v_pk_mul_f32 v[78:79], v[78:79], v[62:63] op_sel_hi:[1,0]
	v_pk_mul_f32 v[90:91], v[58:59], v[62:63] op_sel_hi:[1,0]
	v_pk_mul_f32 v[38:39], v[2:3], v[36:37]
	v_pk_mul_f32 v[36:37], v[0:1], v[60:61]
	v_pk_mul_f32 v[50:51], v[6:7], v[70:71]
	v_pk_mul_f32 v[48:49], v[4:5], v[66:67]
	v_pk_mul_f32 v[54:55], v[10:11], v[72:73]
	v_pk_mul_f32 v[52:53], v[8:9], v[64:65]
	v_pk_mul_f32 v[58:59], v[14:15], v[76:77]
	v_pk_mul_f32 v[56:57], v[12:13], v[68:69]
	v_pk_mul_f32 v[62:63], v[18:19], v[82:83]
	v_pk_mul_f32 v[60:61], v[16:17], v[80:81]
	v_pk_mul_f32 v[66:67], v[22:23], v[86:87]
	v_pk_mul_f32 v[64:65], v[20:21], v[84:85]
	v_pk_mul_f32 v[70:71], v[26:27], v[88:89]
	v_pk_mul_f32 v[68:69], v[24:25], v[74:75]
	v_pk_mul_f32 v[74:75], v[30:31], v[90:91]
	v_pk_mul_f32 v[72:73], v[28:29], v[78:79]
	global_store_dwordx4 v[32:33], v[36:39], off offset:-4096
	global_store_dwordx4 v[32:33], v[48:51], off offset:-3072
	global_store_dwordx4 v[32:33], v[52:55], off offset:-2048
	global_store_dwordx4 v[32:33], v[56:59], off offset:-1024
	global_store_dwordx4 v[32:33], v[60:63], off
	global_store_dwordx4 v[32:33], v[64:67], off offset:1024
	global_store_dwordx4 v[32:33], v[68:71], off offset:2048
	global_store_dwordx4 v[32:33], v[72:75], off offset:3072
	v_lshl_add_u64 v[32:33], v[32:33], 0, s[2:3]
	s_cbranch_scc1 .LBB0_1867
